# v7 schedule regenerated + SGU: no tril masks on fully-unmasked ks blocks
# speedup vs baseline: 1.0488x; 1.0034x over previous
; __device__ __forceinline__ unsigned cvt_pk_bf16(float lo, float hi) { unsigned r; asm volatile("v_cvt_pk_bf16_f32 %0, %1, %2" : "=v"(r) : "v"(lo), "v"(hi)); return r; }
; __device__ __forceinline__ void st16_wt(void* p, u32x4 v) { asm volatile("global_store_dwordx4 %0, %1, off sc1\n\ts_nop 1" :: "v"(p), "v"(v) : "memory"); }
; __device__ __forceinline__ void tr_item(const float* __restrict__ W, int K, int N, bf16_t* WT, const float* __restrict__ kscale, int rowmode, int item, int lane) {
;     const int nblk = N >> 5, kb = item / nblk, nb = item - kb * nblk;
;     const int c = lane >> 3, q = lane & 7, k0 = kb * 64 + c * 8, n0 = nb * 32 + q * 4;
;     f32x4 v[8];
; #pragma unroll
;     for (int i = 0; i < 8; ++i) v[i] = __builtin_nontemporal_load((const f32x4*)(W + (size_t)(k0 + i) * N + n0));
;     if (kscale) { const f32x4 s0 = *(const f32x4*)(kscale + k0), s1 = *(const f32x4*)(kscale + k0 + 4);
; #pragma unroll
;         for (int i = 0; i < 4; ++i) { v[i] = v[i] * s0[i]; v[4 + i] = v[4 + i] * s1[i]; } }
;     int drow;
;     if (rowmode == 0) drow = n0;
;     else if (rowmode == 3) { const int g = n0 - pg8::C_GA; drow = g < 0 ? n0 : pg8::C_GA + (((g & 2047) >> 7) << 8) + ((g >> 11) << 7) + (g & 127); }
;     else drow = ((n0 >> 7) << 8) + (n0 & 127) + (rowmode == 2 ? 128 : 0);
; #pragma unroll
;     for (int e = 0; e < 4; ++e) { u32x4 o; o.x = cvt_pk_bf16(v[0][e], v[1][e]); o.y = cvt_pk_bf16(v[2][e], v[3][e]); o.z = cvt_pk_bf16(v[4][e], v[5][e]); o.w = cvt_pk_bf16(v[6][e], v[7][e]);
;         pg8::st16_wt(WT + (size_t)(drow + e) * K + k0, o); }
; __device__ __forceinline__ void xcd_barrier(const XcdBarrier& b) {
;     ...
;     }
;     __syncthreads();
.LBB0_310:
	s_or_b64 exec, exec, s[6:7]
	s_cmp_lg_u32 s64, 0
	s_cbranch_scc1 .Lcv_skip_1
	v_and_b32_e32 v106, 63, v204
	v_lshrrev_b32_e32 v107, 3, v106
	v_and_b32_e32 v108, 7, v106
	v_readfirstlane_b32 vcc_lo, v204
	s_nop 3
	s_lshr_b32 vcc_lo, vcc_lo, 6
	s_cmp_eq_u32 vcc_lo, 0
	s_cbranch_scc1 .Lcv_skip_1
	s_mul_i32 vcc_hi, s85, 7
	s_add_i32 vcc_lo, vcc_lo, vcc_hi
	s_add_i32 vcc_lo, vcc_lo, -1
	s_add_i32 vcc_lo, vcc_lo, 0
	s_sub_u32 vcc_lo, vcc_lo, 0
	v_mov_b32_e32 v113, vcc_lo
	v_mul_u32_u24_e32 v109, 0x5d18, v113
	v_lshrrev_b32_e32 v109, 22, v109
	v_mul_u32_u24_e32 v110, 0xb0, v109
	v_sub_u32_e32 v110, v113, v110
	v_lshlrev_b32_e32 v109, 6, v109
	v_lshl_add_u32 v109, v107, 3, v109
	v_lshlrev_b32_e32 v110, 5, v110
	v_lshl_add_u32 v110, v108, 2, v110
	v_mul_u32_u24_e32 v111, 0x5800, v109
	v_lshl_add_u32 v111, v110, 2, v111
	v_lshrrev_b32_e32 v112, 7, v110
	v_lshlrev_b32_e32 v112, 8, v112
	v_and_b32_e32 v113, 0x7f, v110
	v_add_u32_e32 v112, v112, v113
	v_lshlrev_b32_e32 v112, 12, v112
	v_lshl_add_u32 v112, v109, 1, v112
	v_lshlrev_b32_e32 v113, 2, v109
	v_readlane_b32 vcc_lo, v250, 28
	v_readlane_b32 vcc_hi, v250, 29
	s_nop 4
	global_load_dwordx4 v[98:101], v113, vcc
	global_load_dwordx4 v[102:105], v113, vcc offset:16
	v_readlane_b32 vcc_lo, v250, 30
	v_readlane_b32 vcc_hi, v250, 31
	s_nop 4
	global_load_dwordx4 v[66:69], v111, vcc nt
	v_add_u32_e32 v111, 0x5800, v111
	global_load_dwordx4 v[70:73], v111, vcc nt
	v_add_u32_e32 v111, 0x5800, v111
	global_load_dwordx4 v[74:77], v111, vcc nt
	v_add_u32_e32 v111, 0x5800, v111
	global_load_dwordx4 v[78:81], v111, vcc nt
	v_add_u32_e32 v111, 0x5800, v111
	global_load_dwordx4 v[82:85], v111, vcc nt
	v_add_u32_e32 v111, 0x5800, v111
	global_load_dwordx4 v[86:89], v111, vcc nt
	v_add_u32_e32 v111, 0x5800, v111
	global_load_dwordx4 v[90:93], v111, vcc nt
	v_add_u32_e32 v111, 0x5800, v111
	global_load_dwordx4 v[94:97], v111, vcc nt
	v_readlane_b32 vcc_lo, v250, 36
	v_readlane_b32 vcc_hi, v250, 37
	s_nop 3
	s_add_u32 vcc_lo, vcc_lo, 0x5dc0000
	s_addc_u32 vcc_hi, vcc_hi, 0
	s_waitcnt vmcnt(0)
	v_mul_f32_e32 v66, v66, v98
	v_mul_f32_e32 v67, v67, v98
	v_mul_f32_e32 v68, v68, v98
	v_mul_f32_e32 v69, v69, v98
	v_mul_f32_e32 v70, v70, v99
	v_mul_f32_e32 v71, v71, v99
	v_mul_f32_e32 v72, v72, v99
	v_mul_f32_e32 v73, v73, v99
	v_mul_f32_e32 v74, v74, v100
	v_mul_f32_e32 v75, v75, v100
	v_mul_f32_e32 v76, v76, v100
	v_mul_f32_e32 v77, v77, v100
	v_mul_f32_e32 v78, v78, v101
	v_mul_f32_e32 v79, v79, v101
	v_mul_f32_e32 v80, v80, v101
	v_mul_f32_e32 v81, v81, v101
	v_mul_f32_e32 v82, v82, v102
	v_mul_f32_e32 v83, v83, v102
	v_mul_f32_e32 v84, v84, v102
	v_mul_f32_e32 v85, v85, v102
	v_mul_f32_e32 v86, v86, v103
	v_mul_f32_e32 v87, v87, v103
	v_mul_f32_e32 v88, v88, v103
	v_mul_f32_e32 v89, v89, v103
	v_mul_f32_e32 v90, v90, v104
	v_mul_f32_e32 v91, v91, v104
	v_mul_f32_e32 v92, v92, v104
	v_mul_f32_e32 v93, v93, v104
	v_mul_f32_e32 v94, v94, v105
	v_mul_f32_e32 v95, v95, v105
	v_mul_f32_e32 v96, v96, v105
	v_mul_f32_e32 v97, v97, v105
	v_cvt_pk_bf16_f32 v114, v66, v70
	v_cvt_pk_bf16_f32 v115, v74, v78
	v_cvt_pk_bf16_f32 v116, v82, v86
	v_cvt_pk_bf16_f32 v117, v90, v94
	v_cvt_pk_bf16_f32 v118, v67, v71
	v_cvt_pk_bf16_f32 v119, v75, v79
	v_cvt_pk_bf16_f32 v120, v83, v87
	v_cvt_pk_bf16_f32 v121, v91, v95
	v_cvt_pk_bf16_f32 v122, v68, v72
	v_cvt_pk_bf16_f32 v123, v76, v80
	v_cvt_pk_bf16_f32 v124, v84, v88
	v_cvt_pk_bf16_f32 v125, v92, v96
	v_cvt_pk_bf16_f32 v126, v69, v73
	v_cvt_pk_bf16_f32 v127, v77, v81
	v_cvt_pk_bf16_f32 v128, v85, v89
	v_cvt_pk_bf16_f32 v129, v93, v97
	global_store_dwordx4 v112, v[114:117], vcc sc1
	v_add_u32_e32 v112, 0x1000, v112
	global_store_dwordx4 v112, v[118:121], vcc sc1
	v_add_u32_e32 v112, 0x1000, v112
	global_store_dwordx4 v112, v[122:125], vcc sc1
	v_add_u32_e32 v112, 0x1000, v112
	global_store_dwordx4 v112, v[126:129], vcc sc1
.Lcv_done_1_0:
.Lcv_skip_1:
	s_mov_b64 s[6:7], 0
	s_waitcnt lgkmcnt(0)
	s_barrier

; __device__ __forceinline__ unsigned cvt_pk_bf16(float lo, float hi) { unsigned r; asm volatile("v_cvt_pk_bf16_f32 %0, %1, %2" : "=v"(r) : "v"(lo), "v"(hi)); return r; }
; #define LAS __attribute__((address_space(3)))
; #define MFMA16(a, b, c) __builtin_amdgcn_mfma_f32_16x16x32_bf16((a), (b), (c), 0, 0, 0)
; __device__ __forceinline__ void p2_block(LAS unsigned char* lds, const bf16_t* __restrict__ PROJ, bf16_t* __restrict__ ATT, bf16_t* __restrict__ SGU, const float* __restrict__ qn, const float* __restrict__ kn, ...
;     ...
;     for (int gi = 0; gi < 2; ++gi) {
;         const int gg = 2 * kvh + gi, irow = 16 * w + fr, nks = (w >> 1) + 1;
;         const LAS unsigned char* VNT = lds + (gi ? VN_OFF1 : VN_OFF0);
;         f32x4 acc[8];
; #pragma unroll
;         for (int dt = 0; dt < 8; ++dt) acc[dt] = (f32x4){0.f, 0.f, 0.f, 0.f};
;         const float* wrow = wsp + (size_t)gg * 16384 + irow * 128 + 8 * fq;
; #pragma unroll
;         for (int ks = 0; ks < 4; ++ks) if (ks < nks) {
;             const f32x4 wa = *(const f32x4*)(wrow + 32 * ks), wb = *(const f32x4*)(wrow + 32 * ks + 4);
;             const int j0 = 32 * ks + 8 * fq; float wv[8];
; #pragma unroll
;             for (int e = 0; e < 4; ++e) { wv[e] = (j0 + e <= irow) ? wa[e] : 0.f; wv[4 + e] = (j0 + 4 + e <= irow) ? wb[e] : 0.f; }
;             u32x4 ww; ww.x = cvt_pk_bf16(wv[0], wv[1]); ww.y = cvt_pk_bf16(wv[2], wv[3]); ww.z = cvt_pk_bf16(wv[4], wv[5]); ww.w = cvt_pk_bf16(wv[6], wv[7]);
;             const bf16x8 wf = __builtin_bit_cast(bf16x8, ww);
; #pragma unroll
;             for (int dt = 0; dt < 8; ++dt) { const bf16x8 af = *(const LAS bf16x8*)(VNT + (16 * dt + fr) * VN_STRIDE + (32 * ks + 8 * fq) * 2); acc[dt] = MFMA16(af, wf, acc[dt]); }
;         }
.Lsgu_n2:
	s_waitcnt vmcnt(8)
	v_mov_b32_e32 v164, v198
	v_mov_b32_e32 v165, v198
	v_mov_b32_e32 v166, v198
	v_mov_b32_e32 v167, v198
	v_mov_b32_e32 v186, v199
	v_mov_b32_e32 v187, v199
	v_mov_b32_e32 v188, v199
	v_mov_b32_e32 v189, v199
	v_cvt_pk_bf16_f32 v144, v98, v99
	v_cvt_pk_bf16_f32 v145, v100, v101
	v_cvt_pk_bf16_f32 v146, v102, v103
	v_cvt_pk_bf16_f32 v147, v104, v105
	v_add_u32_e32 v196, 4294967264, v195
	v_cmp_le_i32_e64 s[40:41], 0, v196
	v_cmp_le_i32_e64 s[42:43], 1, v196
	v_cmp_le_i32_e64 s[44:45], 2, v196
	v_cmp_le_i32_e64 s[46:47], 3, v196
	v_cmp_le_i32_e64 s[48:49], 4, v196
	v_cmp_le_i32_e64 s[50:51], 5, v196
	v_cmp_le_i32_e64 s[52:53], 6, v196
	v_cmp_le_i32_e32 vcc, 7, v196
	v_cndmask_b32_e64 v106, 0, v106, s[40:41]
	v_cndmask_b32_e64 v107, 0, v107, s[42:43]
	v_cndmask_b32_e64 v108, 0, v108, s[44:45]
	v_cndmask_b32_e64 v109, 0, v109, s[46:47]
	v_cndmask_b32_e64 v110, 0, v110, s[48:49]
	v_cndmask_b32_e64 v111, 0, v111, s[50:51]
	v_cndmask_b32_e64 v112, 0, v112, s[52:53]
	v_cndmask_b32_e32 v113, 0, v113, vcc
	v_cvt_pk_bf16_f32 v148, v106, v107
	v_cvt_pk_bf16_f32 v149, v108, v109
	v_cvt_pk_bf16_f32 v150, v110, v111
	v_cvt_pk_bf16_f32 v151, v112, v113
	ds_read_b128 v[34:37], v194 offset:0
	ds_read_b128 v[38:41], v194 offset:4352
	ds_read_b128 v[42:45], v194 offset:8704
	ds_read_b128 v[46:49], v194 offset:13056
	ds_read_b128 v[50:53], v194 offset:17408
	ds_read_b128 v[54:57], v194 offset:21760
	ds_read_b128 v[58:61], v194 offset:26112
	ds_read_b128 v[62:65], v194 offset:30464
	s_waitcnt vmcnt(0)
	v_cvt_pk_bf16_f32 v98, v66, v67
	v_cvt_pk_bf16_f32 v99, v68, v69
	v_cvt_pk_bf16_f32 v100, v70, v71
	v_cvt_pk_bf16_f32 v101, v72, v73
	v_add_u32_e32 v196, 4294967264, v195
	v_cmp_le_i32_e64 s[40:41], 0, v196
	v_cmp_le_i32_e64 s[42:43], 1, v196
	v_cmp_le_i32_e64 s[44:45], 2, v196
	v_cmp_le_i32_e64 s[46:47], 3, v196
	v_cmp_le_i32_e64 s[48:49], 4, v196
	v_cmp_le_i32_e64 s[50:51], 5, v196
	v_cmp_le_i32_e64 s[52:53], 6, v196
	v_cmp_le_i32_e32 vcc, 7, v196
	v_cndmask_b32_e64 v74, 0, v74, s[40:41]
	v_cndmask_b32_e64 v75, 0, v75, s[42:43]
	v_cndmask_b32_e64 v76, 0, v76, s[44:45]
	v_cndmask_b32_e64 v77, 0, v77, s[46:47]
	v_cndmask_b32_e64 v78, 0, v78, s[48:49]
	v_cndmask_b32_e64 v79, 0, v79, s[50:51]
	v_cndmask_b32_e64 v80, 0, v80, s[52:53]
	v_cndmask_b32_e32 v81, 0, v81, vcc
	v_cvt_pk_bf16_f32 v102, v74, v75
	v_cvt_pk_bf16_f32 v103, v76, v77
	v_cvt_pk_bf16_f32 v104, v78, v79
	v_cvt_pk_bf16_f32 v105, v80, v81
	ds_read_b128 v[66:69], v194 offset:64
	ds_read_b128 v[70:73], v194 offset:4416
	ds_read_b128 v[74:77], v194 offset:8768
	ds_read_b128 v[78:81], v194 offset:13120
	ds_read_b128 v[82:85], v194 offset:17472
	ds_read_b128 v[86:89], v194 offset:21824
	ds_read_b128 v[90:93], v194 offset:26176
	ds_read_b128 v[94:97], v194 offset:30528
	s_waitcnt lgkmcnt(15)
	v_mfma_f32_16x16x32_bf16 v[2:5], v[34:37], v[144:147], v[164:167]
	s_waitcnt lgkmcnt(14)
	v_mfma_f32_16x16x32_bf16 v[6:9], v[38:41], v[144:147], v[164:167]
	s_waitcnt lgkmcnt(13)
	v_mfma_f32_16x16x32_bf16 v[10:13], v[42:45], v[144:147], v[164:167]
	s_waitcnt lgkmcnt(12)
	v_mfma_f32_16x16x32_bf16 v[14:17], v[46:49], v[144:147], v[164:167]
	s_waitcnt lgkmcnt(11)
	v_mfma_f32_16x16x32_bf16 v[18:21], v[50:53], v[144:147], v[164:167]
	s_waitcnt lgkmcnt(10)
	v_mfma_f32_16x16x32_bf16 v[22:25], v[54:57], v[144:147], v[164:167]
	s_waitcnt lgkmcnt(9)
	v_mfma_f32_16x16x32_bf16 v[26:29], v[58:61], v[144:147], v[164:167]
	s_waitcnt lgkmcnt(8)
	v_mfma_f32_16x16x32_bf16 v[30:33], v[62:65], v[144:147], v[164:167]
	ds_read_b128 v[34:37], v194 offset:34816
	ds_read_b128 v[38:41], v194 offset:39168
	ds_read_b128 v[42:45], v194 offset:43520
	ds_read_b128 v[46:49], v194 offset:47872
	ds_read_b128 v[50:53], v194 offset:52224
	ds_read_b128 v[54:57], v194 offset:56576
	ds_read_b128 v[58:61], v194 offset:60928
	ds_read_b128 v[62:65], v194 offset:65280
	s_waitcnt lgkmcnt(15)
	v_mfma_f32_16x16x32_bf16 v[2:5], v[66:69], v[148:151], v[2:5]
	s_waitcnt lgkmcnt(14)
	v_mfma_f32_16x16x32_bf16 v[6:9], v[70:73], v[148:151], v[6:9]
	s_waitcnt lgkmcnt(13)
	v_mfma_f32_16x16x32_bf16 v[10:13], v[74:77], v[148:151], v[10:13]
	s_waitcnt lgkmcnt(12)
	v_mfma_f32_16x16x32_bf16 v[14:17], v[78:81], v[148:151], v[14:17]
	s_waitcnt lgkmcnt(11)
	v_mfma_f32_16x16x32_bf16 v[18:21], v[82:85], v[148:151], v[18:21]
	s_waitcnt lgkmcnt(10)
	v_mfma_f32_16x16x32_bf16 v[22:25], v[86:89], v[148:151], v[22:25]
	s_waitcnt lgkmcnt(9)
	v_mfma_f32_16x16x32_bf16 v[26:29], v[90:93], v[148:151], v[26:29]
	s_waitcnt lgkmcnt(8)
	v_mfma_f32_16x16x32_bf16 v[30:33], v[94:97], v[148:151], v[30:33]
	ds_read_b128 v[66:69], v194 offset:34880
	ds_read_b128 v[70:73], v194 offset:39232
	ds_read_b128 v[74:77], v194 offset:43584
	ds_read_b128 v[78:81], v194 offset:47936
	ds_read_b128 v[82:85], v194 offset:52288
	ds_read_b128 v[86:89], v194 offset:56640
	ds_read_b128 v[90:93], v194 offset:60992
	ds_read_b128 v[94:97], v194 offset:65344
	s_waitcnt lgkmcnt(15)
	v_mfma_f32_16x16x32_bf16 v[114:117], v[34:37], v[98:101], v[186:189]
	s_waitcnt lgkmcnt(14)
	v_mfma_f32_16x16x32_bf16 v[118:121], v[38:41], v[98:101], v[186:189]
	s_waitcnt lgkmcnt(13)
	v_mfma_f32_16x16x32_bf16 v[122:125], v[42:45], v[98:101], v[186:189]
	s_waitcnt lgkmcnt(12)
	v_mfma_f32_16x16x32_bf16 v[126:129], v[46:49], v[98:101], v[186:189]
	s_waitcnt lgkmcnt(11)
	v_mfma_f32_16x16x32_bf16 v[130:133], v[50:53], v[98:101], v[186:189]
	s_waitcnt lgkmcnt(10)
	v_mfma_f32_16x16x32_bf16 v[134:137], v[54:57], v[98:101], v[186:189]
	s_waitcnt lgkmcnt(9)
	v_mfma_f32_16x16x32_bf16 v[138:141], v[58:61], v[98:101], v[186:189]
	s_waitcnt lgkmcnt(8)
	v_mfma_f32_16x16x32_bf16 v[160:163], v[62:65], v[98:101], v[186:189]
	s_waitcnt lgkmcnt(7)
	v_mfma_f32_16x16x32_bf16 v[114:117], v[66:69], v[102:105], v[114:117]
	s_waitcnt lgkmcnt(6)
	v_mfma_f32_16x16x32_bf16 v[118:121], v[70:73], v[102:105], v[118:121]
	s_waitcnt lgkmcnt(5)
	v_mfma_f32_16x16x32_bf16 v[122:125], v[74:77], v[102:105], v[122:125]
	s_waitcnt lgkmcnt(4)
	v_mfma_f32_16x16x32_bf16 v[126:129], v[78:81], v[102:105], v[126:129]
	s_waitcnt lgkmcnt(3)
	v_mfma_f32_16x16x32_bf16 v[130:133], v[82:85], v[102:105], v[130:133]
	s_waitcnt lgkmcnt(2)
	v_mfma_f32_16x16x32_bf16 v[134:137], v[86:89], v[102:105], v[134:137]
	s_waitcnt lgkmcnt(1)
	v_mfma_f32_16x16x32_bf16 v[138:141], v[90:93], v[102:105], v[138:141]
	s_waitcnt lgkmcnt(0)
	v_mfma_f32_16x16x32_bf16 v[160:163], v[94:97], v[102:105], v[160:163]
	s_branch .Lsgu_epi
; __device__ __forceinline__ unsigned cvt_pk_bf16(float lo, float hi) { unsigned r; asm volatile("v_cvt_pk_bf16_f32 %0, %1, %2" : "=v"(r) : "v"(lo), "v"(hi)); return r; }
; #define LAS __attribute__((address_space(3)))
; #define MFMA16(a, b, c) __builtin_amdgcn_mfma_f32_16x16x32_bf16((a), (b), (c), 0, 0, 0)
; __device__ __forceinline__ void p2_block(LAS unsigned char* lds, const bf16_t* __restrict__ PROJ, bf16_t* __restrict__ ATT, bf16_t* __restrict__ SGU, const float* __restrict__ qn, const float* __restrict__ kn, ...
;     ...
;     for (int gi = 0; gi < 2; ++gi) {
;         const int gg = 2 * kvh + gi, irow = 16 * w + fr, nks = (w >> 1) + 1;
;         const LAS unsigned char* VNT = lds + (gi ? VN_OFF1 : VN_OFF0);
;         f32x4 acc[8];
; #pragma unroll
;         for (int dt = 0; dt < 8; ++dt) acc[dt] = (f32x4){0.f, 0.f, 0.f, 0.f};
;         const float* wrow = wsp + (size_t)gg * 16384 + irow * 128 + 8 * fq;
; #pragma unroll
;         for (int ks = 0; ks < 4; ++ks) if (ks < nks) {
;             const f32x4 wa = *(const f32x4*)(wrow + 32 * ks), wb = *(const f32x4*)(wrow + 32 * ks + 4);
;             const int j0 = 32 * ks + 8 * fq; float wv[8];
; #pragma unroll
;             for (int e = 0; e < 4; ++e) { wv[e] = (j0 + e <= irow) ? wa[e] : 0.f; wv[4 + e] = (j0 + 4 + e <= irow) ? wb[e] : 0.f; }
;             u32x4 ww; ww.x = cvt_pk_bf16(wv[0], wv[1]); ww.y = cvt_pk_bf16(wv[2], wv[3]); ww.z = cvt_pk_bf16(wv[4], wv[5]); ww.w = cvt_pk_bf16(wv[6], wv[7]);
;             const bf16x8 wf = __builtin_bit_cast(bf16x8, ww);
; #pragma unroll
;             for (int dt = 0; dt < 8; ++dt) { const bf16x8 af = *(const LAS bf16x8*)(VNT + (16 * dt + fr) * VN_STRIDE + (32 * ks + 8 * fq) * 2); acc[dt] = MFMA16(af, wf, acc[dt]); }
;         }
.Lsgu_n3:
	s_waitcnt vmcnt(8)
	v_mov_b32_e32 v164, v198
	v_mov_b32_e32 v165, v198
	v_mov_b32_e32 v166, v198
	v_mov_b32_e32 v167, v198
	v_mov_b32_e32 v186, v199
	v_mov_b32_e32 v187, v199
	v_mov_b32_e32 v188, v199
	v_mov_b32_e32 v189, v199
	v_cvt_pk_bf16_f32 v144, v98, v99
	v_cvt_pk_bf16_f32 v145, v100, v101
	v_cvt_pk_bf16_f32 v146, v102, v103
	v_cvt_pk_bf16_f32 v147, v104, v105
	v_cvt_pk_bf16_f32 v148, v106, v107
	v_cvt_pk_bf16_f32 v149, v108, v109
	v_cvt_pk_bf16_f32 v150, v110, v111
	v_cvt_pk_bf16_f32 v151, v112, v113
	v_add_u32_e32 v196, 4294967232, v195
	v_cmp_le_i32_e64 s[40:41], 0, v196
	v_cmp_le_i32_e64 s[42:43], 1, v196
	v_cmp_le_i32_e64 s[44:45], 2, v196
	v_cmp_le_i32_e64 s[46:47], 3, v196
	v_cmp_le_i32_e64 s[48:49], 4, v196
	v_cmp_le_i32_e64 s[50:51], 5, v196
	v_cmp_le_i32_e64 s[52:53], 6, v196
	v_cmp_le_i32_e32 vcc, 7, v196
	v_cndmask_b32_e64 v114, 0, v114, s[40:41]
	v_cndmask_b32_e64 v115, 0, v115, s[42:43]
	v_cndmask_b32_e64 v116, 0, v116, s[44:45]
	v_cndmask_b32_e64 v117, 0, v117, s[46:47]
	v_cndmask_b32_e64 v118, 0, v118, s[48:49]
	v_cndmask_b32_e64 v119, 0, v119, s[50:51]
	v_cndmask_b32_e64 v120, 0, v120, s[52:53]
	v_cndmask_b32_e32 v121, 0, v121, vcc
	v_cvt_pk_bf16_f32 v152, v114, v115
	v_cvt_pk_bf16_f32 v153, v116, v117
	v_cvt_pk_bf16_f32 v154, v118, v119
	v_cvt_pk_bf16_f32 v155, v120, v121
	ds_read_b128 v[34:37], v194 offset:0
	ds_read_b128 v[38:41], v194 offset:4352
	ds_read_b128 v[42:45], v194 offset:8704
	ds_read_b128 v[46:49], v194 offset:13056
	ds_read_b128 v[50:53], v194 offset:17408
	ds_read_b128 v[54:57], v194 offset:21760
	ds_read_b128 v[58:61], v194 offset:26112
	ds_read_b128 v[62:65], v194 offset:30464
	s_waitcnt vmcnt(0)
	v_cvt_pk_bf16_f32 v98, v66, v67
	v_cvt_pk_bf16_f32 v99, v68, v69
	v_cvt_pk_bf16_f32 v100, v70, v71
	v_cvt_pk_bf16_f32 v101, v72, v73
	v_cvt_pk_bf16_f32 v102, v74, v75
	v_cvt_pk_bf16_f32 v103, v76, v77
	v_cvt_pk_bf16_f32 v104, v78, v79
	v_cvt_pk_bf16_f32 v105, v80, v81
	v_add_u32_e32 v196, 4294967232, v195
	v_cmp_le_i32_e64 s[40:41], 0, v196
	v_cmp_le_i32_e64 s[42:43], 1, v196
	v_cmp_le_i32_e64 s[44:45], 2, v196
	v_cmp_le_i32_e64 s[46:47], 3, v196
	v_cmp_le_i32_e64 s[48:49], 4, v196
	v_cmp_le_i32_e64 s[50:51], 5, v196
	v_cmp_le_i32_e64 s[52:53], 6, v196
	v_cmp_le_i32_e32 vcc, 7, v196
	v_cndmask_b32_e64 v82, 0, v82, s[40:41]
	v_cndmask_b32_e64 v83, 0, v83, s[42:43]
	v_cndmask_b32_e64 v84, 0, v84, s[44:45]
	v_cndmask_b32_e64 v85, 0, v85, s[46:47]
	v_cndmask_b32_e64 v86, 0, v86, s[48:49]
	v_cndmask_b32_e64 v87, 0, v87, s[50:51]
	v_cndmask_b32_e64 v88, 0, v88, s[52:53]
	v_cndmask_b32_e32 v89, 0, v89, vcc
	v_cvt_pk_bf16_f32 v106, v82, v83
	v_cvt_pk_bf16_f32 v107, v84, v85
	v_cvt_pk_bf16_f32 v108, v86, v87
	v_cvt_pk_bf16_f32 v109, v88, v89
	ds_read_b128 v[66:69], v194 offset:64
	ds_read_b128 v[70:73], v194 offset:4416
	ds_read_b128 v[74:77], v194 offset:8768
	ds_read_b128 v[78:81], v194 offset:13120
	ds_read_b128 v[82:85], v194 offset:17472
	ds_read_b128 v[86:89], v194 offset:21824
	ds_read_b128 v[90:93], v194 offset:26176
	ds_read_b128 v[94:97], v194 offset:30528
	s_waitcnt lgkmcnt(15)
	v_mfma_f32_16x16x32_bf16 v[2:5], v[34:37], v[144:147], v[164:167]
	s_waitcnt lgkmcnt(14)
	v_mfma_f32_16x16x32_bf16 v[6:9], v[38:41], v[144:147], v[164:167]
	s_waitcnt lgkmcnt(13)
	v_mfma_f32_16x16x32_bf16 v[10:13], v[42:45], v[144:147], v[164:167]
	s_waitcnt lgkmcnt(12)
	v_mfma_f32_16x16x32_bf16 v[14:17], v[46:49], v[144:147], v[164:167]
	s_waitcnt lgkmcnt(11)
	v_mfma_f32_16x16x32_bf16 v[18:21], v[50:53], v[144:147], v[164:167]
	s_waitcnt lgkmcnt(10)
	v_mfma_f32_16x16x32_bf16 v[22:25], v[54:57], v[144:147], v[164:167]
	s_waitcnt lgkmcnt(9)
	v_mfma_f32_16x16x32_bf16 v[26:29], v[58:61], v[144:147], v[164:167]
	s_waitcnt lgkmcnt(8)
	v_mfma_f32_16x16x32_bf16 v[30:33], v[62:65], v[144:147], v[164:167]
	ds_read_b128 v[34:37], v194 offset:128
	ds_read_b128 v[38:41], v194 offset:4480
	ds_read_b128 v[42:45], v194 offset:8832
	ds_read_b128 v[46:49], v194 offset:13184
	ds_read_b128 v[50:53], v194 offset:17536
	ds_read_b128 v[54:57], v194 offset:21888
	ds_read_b128 v[58:61], v194 offset:26240
	ds_read_b128 v[62:65], v194 offset:30592
	s_waitcnt lgkmcnt(15)
	v_mfma_f32_16x16x32_bf16 v[2:5], v[66:69], v[148:151], v[2:5]
	s_waitcnt lgkmcnt(14)
	v_mfma_f32_16x16x32_bf16 v[6:9], v[70:73], v[148:151], v[6:9]
	s_waitcnt lgkmcnt(13)
	v_mfma_f32_16x16x32_bf16 v[10:13], v[74:77], v[148:151], v[10:13]
	s_waitcnt lgkmcnt(12)
	v_mfma_f32_16x16x32_bf16 v[14:17], v[78:81], v[148:151], v[14:17]
	s_waitcnt lgkmcnt(11)
	v_mfma_f32_16x16x32_bf16 v[18:21], v[82:85], v[148:151], v[18:21]
	s_waitcnt lgkmcnt(10)
	v_mfma_f32_16x16x32_bf16 v[22:25], v[86:89], v[148:151], v[22:25]
	s_waitcnt lgkmcnt(9)
	v_mfma_f32_16x16x32_bf16 v[26:29], v[90:93], v[148:151], v[26:29]
	s_waitcnt lgkmcnt(8)
	v_mfma_f32_16x16x32_bf16 v[30:33], v[94:97], v[148:151], v[30:33]
	ds_read_b128 v[66:69], v194 offset:34816
	ds_read_b128 v[70:73], v194 offset:39168
	ds_read_b128 v[74:77], v194 offset:43520
	ds_read_b128 v[78:81], v194 offset:47872
	ds_read_b128 v[82:85], v194 offset:52224
	ds_read_b128 v[86:89], v194 offset:56576
	ds_read_b128 v[90:93], v194 offset:60928
	ds_read_b128 v[94:97], v194 offset:65280
	s_waitcnt lgkmcnt(15)
	v_mfma_f32_16x16x32_bf16 v[2:5], v[34:37], v[152:155], v[2:5]
	s_waitcnt lgkmcnt(14)
	v_mfma_f32_16x16x32_bf16 v[6:9], v[38:41], v[152:155], v[6:9]
	s_waitcnt lgkmcnt(13)
	v_mfma_f32_16x16x32_bf16 v[10:13], v[42:45], v[152:155], v[10:13]
	s_waitcnt lgkmcnt(12)
	v_mfma_f32_16x16x32_bf16 v[14:17], v[46:49], v[152:155], v[14:17]
	s_waitcnt lgkmcnt(11)
	v_mfma_f32_16x16x32_bf16 v[18:21], v[50:53], v[152:155], v[18:21]
	s_waitcnt lgkmcnt(10)
; __device__ __forceinline__ unsigned cvt_pk_bf16(float lo, float hi) { unsigned r; asm volatile("v_cvt_pk_bf16_f32 %0, %1, %2" : "=v"(r) : "v"(lo), "v"(hi)); return r; }
; #define LAS __attribute__((address_space(3)))
; #define MFMA16(a, b, c) __builtin_amdgcn_mfma_f32_16x16x32_bf16((a), (b), (c), 0, 0, 0)
; __device__ __forceinline__ void p2_block(LAS unsigned char* lds, const bf16_t* __restrict__ PROJ, bf16_t* __restrict__ ATT, bf16_t* __restrict__ SGU, const float* __restrict__ qn, const float* __restrict__ kn, ...
;     ...
;     for (int gi = 0; gi < 2; ++gi) {
;         const int gg = 2 * kvh + gi, irow = 16 * w + fr, nks = (w >> 1) + 1;
;         const LAS unsigned char* VNT = lds + (gi ? VN_OFF1 : VN_OFF0);
;         f32x4 acc[8];
; #pragma unroll
;         for (int dt = 0; dt < 8; ++dt) acc[dt] = (f32x4){0.f, 0.f, 0.f, 0.f};
;         const float* wrow = wsp + (size_t)gg * 16384 + irow * 128 + 8 * fq;
; #pragma unroll
;         for (int ks = 0; ks < 4; ++ks) if (ks < nks) {
;             const f32x4 wa = *(const f32x4*)(wrow + 32 * ks), wb = *(const f32x4*)(wrow + 32 * ks + 4);
;             const int j0 = 32 * ks + 8 * fq; float wv[8];
; #pragma unroll
;             for (int e = 0; e < 4; ++e) { wv[e] = (j0 + e <= irow) ? wa[e] : 0.f; wv[4 + e] = (j0 + 4 + e <= irow) ? wb[e] : 0.f; }
;             u32x4 ww; ww.x = cvt_pk_bf16(wv[0], wv[1]); ww.y = cvt_pk_bf16(wv[2], wv[3]); ww.z = cvt_pk_bf16(wv[4], wv[5]); ww.w = cvt_pk_bf16(wv[6], wv[7]);
;             const bf16x8 wf = __builtin_bit_cast(bf16x8, ww);
; #pragma unroll
;             for (int dt = 0; dt < 8; ++dt) { const bf16x8 af = *(const LAS bf16x8*)(VNT + (16 * dt + fr) * VN_STRIDE + (32 * ks + 8 * fq) * 2); acc[dt] = MFMA16(af, wf, acc[dt]); }
;         }
	v_mfma_f32_16x16x32_bf16 v[22:25], v[54:57], v[152:155], v[22:25]
	s_waitcnt lgkmcnt(9)
	v_mfma_f32_16x16x32_bf16 v[26:29], v[58:61], v[152:155], v[26:29]
	s_waitcnt lgkmcnt(8)
	v_mfma_f32_16x16x32_bf16 v[30:33], v[62:65], v[152:155], v[30:33]
	ds_read_b128 v[34:37], v194 offset:34880
	ds_read_b128 v[38:41], v194 offset:39232
	ds_read_b128 v[42:45], v194 offset:43584
	ds_read_b128 v[46:49], v194 offset:47936
	ds_read_b128 v[50:53], v194 offset:52288
	ds_read_b128 v[54:57], v194 offset:56640
	ds_read_b128 v[58:61], v194 offset:60992
	ds_read_b128 v[62:65], v194 offset:65344
	s_waitcnt lgkmcnt(15)
	v_mfma_f32_16x16x32_bf16 v[114:117], v[66:69], v[98:101], v[186:189]
	s_waitcnt lgkmcnt(14)
	v_mfma_f32_16x16x32_bf16 v[118:121], v[70:73], v[98:101], v[186:189]
	s_waitcnt lgkmcnt(13)
	v_mfma_f32_16x16x32_bf16 v[122:125], v[74:77], v[98:101], v[186:189]
	s_waitcnt lgkmcnt(12)
	v_mfma_f32_16x16x32_bf16 v[126:129], v[78:81], v[98:101], v[186:189]
	s_waitcnt lgkmcnt(11)
	v_mfma_f32_16x16x32_bf16 v[130:133], v[82:85], v[98:101], v[186:189]
	s_waitcnt lgkmcnt(10)
	v_mfma_f32_16x16x32_bf16 v[134:137], v[86:89], v[98:101], v[186:189]
	s_waitcnt lgkmcnt(9)
	v_mfma_f32_16x16x32_bf16 v[138:141], v[90:93], v[98:101], v[186:189]
	s_waitcnt lgkmcnt(8)
	v_mfma_f32_16x16x32_bf16 v[160:163], v[94:97], v[98:101], v[186:189]
	ds_read_b128 v[66:69], v194 offset:34944
	ds_read_b128 v[70:73], v194 offset:39296
	ds_read_b128 v[74:77], v194 offset:43648
	ds_read_b128 v[78:81], v194 offset:48000
	ds_read_b128 v[82:85], v194 offset:52352
	ds_read_b128 v[86:89], v194 offset:56704
	ds_read_b128 v[90:93], v194 offset:61056
	ds_read_b128 v[94:97], v194 offset:65408
	s_waitcnt lgkmcnt(15)
	v_mfma_f32_16x16x32_bf16 v[114:117], v[34:37], v[102:105], v[114:117]
	s_waitcnt lgkmcnt(14)
	v_mfma_f32_16x16x32_bf16 v[118:121], v[38:41], v[102:105], v[118:121]
	s_waitcnt lgkmcnt(13)
	v_mfma_f32_16x16x32_bf16 v[122:125], v[42:45], v[102:105], v[122:125]
	s_waitcnt lgkmcnt(12)
	v_mfma_f32_16x16x32_bf16 v[126:129], v[46:49], v[102:105], v[126:129]
	s_waitcnt lgkmcnt(11)
	v_mfma_f32_16x16x32_bf16 v[130:133], v[50:53], v[102:105], v[130:133]
	s_waitcnt lgkmcnt(10)
	v_mfma_f32_16x16x32_bf16 v[134:137], v[54:57], v[102:105], v[134:137]
	s_waitcnt lgkmcnt(9)
	v_mfma_f32_16x16x32_bf16 v[138:141], v[58:61], v[102:105], v[138:141]
	s_waitcnt lgkmcnt(8)
	v_mfma_f32_16x16x32_bf16 v[160:163], v[62:65], v[102:105], v[160:163]
	s_waitcnt lgkmcnt(7)
	v_mfma_f32_16x16x32_bf16 v[114:117], v[66:69], v[106:109], v[114:117]
	s_waitcnt lgkmcnt(6)
	v_mfma_f32_16x16x32_bf16 v[118:121], v[70:73], v[106:109], v[118:121]
	s_waitcnt lgkmcnt(5)
	v_mfma_f32_16x16x32_bf16 v[122:125], v[74:77], v[106:109], v[122:125]
	s_waitcnt lgkmcnt(4)
	v_mfma_f32_16x16x32_bf16 v[126:129], v[78:81], v[106:109], v[126:129]
	s_waitcnt lgkmcnt(3)
	v_mfma_f32_16x16x32_bf16 v[130:133], v[82:85], v[106:109], v[130:133]
	s_waitcnt lgkmcnt(2)
	v_mfma_f32_16x16x32_bf16 v[134:137], v[86:89], v[106:109], v[134:137]
	s_waitcnt lgkmcnt(1)
	v_mfma_f32_16x16x32_bf16 v[138:141], v[90:93], v[106:109], v[138:141]
	s_waitcnt lgkmcnt(0)
	v_mfma_f32_16x16x32_bf16 v[160:163], v[94:97], v[106:109], v[160:163]
	s_branch .Lsgu_epi
.Lsgu_n4:
	s_waitcnt vmcnt(8)
	v_mov_b32_e32 v164, v198
	v_mov_b32_e32 v165, v198
	v_mov_b32_e32 v166, v198
	v_mov_b32_e32 v167, v198
	v_mov_b32_e32 v186, v199
	v_mov_b32_e32 v187, v199
	v_mov_b32_e32 v188, v199
	v_mov_b32_e32 v189, v199
	v_cvt_pk_bf16_f32 v144, v98, v99
	v_cvt_pk_bf16_f32 v145, v100, v101
	v_cvt_pk_bf16_f32 v146, v102, v103
	v_cvt_pk_bf16_f32 v147, v104, v105
	v_cvt_pk_bf16_f32 v148, v106, v107
	v_cvt_pk_bf16_f32 v149, v108, v109
	v_cvt_pk_bf16_f32 v150, v110, v111
	v_cvt_pk_bf16_f32 v151, v112, v113
	v_cvt_pk_bf16_f32 v152, v114, v115
	v_cvt_pk_bf16_f32 v153, v116, v117
	v_cvt_pk_bf16_f32 v154, v118, v119
	v_cvt_pk_bf16_f32 v155, v120, v121
	v_add_u32_e32 v196, 4294967200, v195
	v_cmp_le_i32_e64 s[40:41], 0, v196
	v_cmp_le_i32_e64 s[42:43], 1, v196
	v_cmp_le_i32_e64 s[44:45], 2, v196
	v_cmp_le_i32_e64 s[46:47], 3, v196
	v_cmp_le_i32_e64 s[48:49], 4, v196
	v_cmp_le_i32_e64 s[50:51], 5, v196
	v_cmp_le_i32_e64 s[52:53], 6, v196
	v_cmp_le_i32_e32 vcc, 7, v196
	v_cndmask_b32_e64 v122, 0, v122, s[40:41]
	v_cndmask_b32_e64 v123, 0, v123, s[42:43]
	v_cndmask_b32_e64 v124, 0, v124, s[44:45]
	v_cndmask_b32_e64 v125, 0, v125, s[46:47]
	v_cndmask_b32_e64 v126, 0, v126, s[48:49]
	v_cndmask_b32_e64 v127, 0, v127, s[50:51]
	v_cndmask_b32_e64 v128, 0, v128, s[52:53]
	v_cndmask_b32_e32 v129, 0, v129, vcc
	v_cvt_pk_bf16_f32 v156, v122, v123
	v_cvt_pk_bf16_f32 v157, v124, v125
	v_cvt_pk_bf16_f32 v158, v126, v127
	v_cvt_pk_bf16_f32 v159, v128, v129
	ds_read_b128 v[34:37], v194 offset:0
	ds_read_b128 v[38:41], v194 offset:4352
	ds_read_b128 v[42:45], v194 offset:8704
	ds_read_b128 v[46:49], v194 offset:13056
	ds_read_b128 v[50:53], v194 offset:17408
	ds_read_b128 v[54:57], v194 offset:21760
	ds_read_b128 v[58:61], v194 offset:26112
	ds_read_b128 v[62:65], v194 offset:30464
	s_waitcnt vmcnt(0)
; __device__ __forceinline__ unsigned cvt_pk_bf16(float lo, float hi) { unsigned r; asm volatile("v_cvt_pk_bf16_f32 %0, %1, %2" : "=v"(r) : "v"(lo), "v"(hi)); return r; }
; #define LAS __attribute__((address_space(3)))
; #define MFMA16(a, b, c) __builtin_amdgcn_mfma_f32_16x16x32_bf16((a), (b), (c), 0, 0, 0)
; __device__ __forceinline__ void p2_block(LAS unsigned char* lds, const bf16_t* __restrict__ PROJ, bf16_t* __restrict__ ATT, bf16_t* __restrict__ SGU, const float* __restrict__ qn, const float* __restrict__ kn, ...
;     ...
;     for (int gi = 0; gi < 2; ++gi) {
;         const int gg = 2 * kvh + gi, irow = 16 * w + fr, nks = (w >> 1) + 1;
;         const LAS unsigned char* VNT = lds + (gi ? VN_OFF1 : VN_OFF0);
;         f32x4 acc[8];
; #pragma unroll
;         for (int dt = 0; dt < 8; ++dt) acc[dt] = (f32x4){0.f, 0.f, 0.f, 0.f};
;         const float* wrow = wsp + (size_t)gg * 16384 + irow * 128 + 8 * fq;
; #pragma unroll
;         for (int ks = 0; ks < 4; ++ks) if (ks < nks) {
;             const f32x4 wa = *(const f32x4*)(wrow + 32 * ks), wb = *(const f32x4*)(wrow + 32 * ks + 4);
;             const int j0 = 32 * ks + 8 * fq; float wv[8];
; #pragma unroll
;             for (int e = 0; e < 4; ++e) { wv[e] = (j0 + e <= irow) ? wa[e] : 0.f; wv[4 + e] = (j0 + 4 + e <= irow) ? wb[e] : 0.f; }
;             u32x4 ww; ww.x = cvt_pk_bf16(wv[0], wv[1]); ww.y = cvt_pk_bf16(wv[2], wv[3]); ww.z = cvt_pk_bf16(wv[4], wv[5]); ww.w = cvt_pk_bf16(wv[6], wv[7]);
;             const bf16x8 wf = __builtin_bit_cast(bf16x8, ww);
; #pragma unroll
;             for (int dt = 0; dt < 8; ++dt) { const bf16x8 af = *(const LAS bf16x8*)(VNT + (16 * dt + fr) * VN_STRIDE + (32 * ks + 8 * fq) * 2); acc[dt] = MFMA16(af, wf, acc[dt]); }
;         }
	v_cvt_pk_bf16_f32 v98, v66, v67
	v_cvt_pk_bf16_f32 v99, v68, v69
	v_cvt_pk_bf16_f32 v100, v70, v71
	v_cvt_pk_bf16_f32 v101, v72, v73
	v_cvt_pk_bf16_f32 v102, v74, v75
	v_cvt_pk_bf16_f32 v103, v76, v77
	v_cvt_pk_bf16_f32 v104, v78, v79
	v_cvt_pk_bf16_f32 v105, v80, v81
	v_cvt_pk_bf16_f32 v106, v82, v83
	v_cvt_pk_bf16_f32 v107, v84, v85
	v_cvt_pk_bf16_f32 v108, v86, v87
	v_cvt_pk_bf16_f32 v109, v88, v89
	v_add_u32_e32 v196, 4294967200, v195
	v_cmp_le_i32_e64 s[40:41], 0, v196
	v_cmp_le_i32_e64 s[42:43], 1, v196
	v_cmp_le_i32_e64 s[44:45], 2, v196
	v_cmp_le_i32_e64 s[46:47], 3, v196
	v_cmp_le_i32_e64 s[48:49], 4, v196
	v_cmp_le_i32_e64 s[50:51], 5, v196
	v_cmp_le_i32_e64 s[52:53], 6, v196
	v_cmp_le_i32_e32 vcc, 7, v196
	v_cndmask_b32_e64 v90, 0, v90, s[40:41]
	v_cndmask_b32_e64 v91, 0, v91, s[42:43]
	v_cndmask_b32_e64 v92, 0, v92, s[44:45]
	v_cndmask_b32_e64 v93, 0, v93, s[46:47]
	v_cndmask_b32_e64 v94, 0, v94, s[48:49]
	v_cndmask_b32_e64 v95, 0, v95, s[50:51]
	v_cndmask_b32_e64 v96, 0, v96, s[52:53]
	v_cndmask_b32_e32 v97, 0, v97, vcc
	v_cvt_pk_bf16_f32 v110, v90, v91
	v_cvt_pk_bf16_f32 v111, v92, v93
	v_cvt_pk_bf16_f32 v112, v94, v95
	v_cvt_pk_bf16_f32 v113, v96, v97
	ds_read_b128 v[66:69], v194 offset:64
	ds_read_b128 v[70:73], v194 offset:4416
	ds_read_b128 v[74:77], v194 offset:8768
	ds_read_b128 v[78:81], v194 offset:13120
	ds_read_b128 v[82:85], v194 offset:17472
	ds_read_b128 v[86:89], v194 offset:21824
	ds_read_b128 v[90:93], v194 offset:26176
	ds_read_b128 v[94:97], v194 offset:30528
	s_waitcnt lgkmcnt(15)
	v_mfma_f32_16x16x32_bf16 v[2:5], v[34:37], v[144:147], v[164:167]
	s_waitcnt lgkmcnt(14)
	v_mfma_f32_16x16x32_bf16 v[6:9], v[38:41], v[144:147], v[164:167]
	s_waitcnt lgkmcnt(13)
	v_mfma_f32_16x16x32_bf16 v[10:13], v[42:45], v[144:147], v[164:167]
	s_waitcnt lgkmcnt(12)
	v_mfma_f32_16x16x32_bf16 v[14:17], v[46:49], v[144:147], v[164:167]
	s_waitcnt lgkmcnt(11)
	v_mfma_f32_16x16x32_bf16 v[18:21], v[50:53], v[144:147], v[164:167]
	s_waitcnt lgkmcnt(10)
	v_mfma_f32_16x16x32_bf16 v[22:25], v[54:57], v[144:147], v[164:167]
	s_waitcnt lgkmcnt(9)
	v_mfma_f32_16x16x32_bf16 v[26:29], v[58:61], v[144:147], v[164:167]
	s_waitcnt lgkmcnt(8)
	v_mfma_f32_16x16x32_bf16 v[30:33], v[62:65], v[144:147], v[164:167]
	ds_read_b128 v[34:37], v194 offset:128
	ds_read_b128 v[38:41], v194 offset:4480
	ds_read_b128 v[42:45], v194 offset:8832
	ds_read_b128 v[46:49], v194 offset:13184
	ds_read_b128 v[50:53], v194 offset:17536
	ds_read_b128 v[54:57], v194 offset:21888
	ds_read_b128 v[58:61], v194 offset:26240
	ds_read_b128 v[62:65], v194 offset:30592
	s_waitcnt lgkmcnt(15)
	v_mfma_f32_16x16x32_bf16 v[2:5], v[66:69], v[148:151], v[2:5]
	s_waitcnt lgkmcnt(14)
	v_mfma_f32_16x16x32_bf16 v[6:9], v[70:73], v[148:151], v[6:9]
	s_waitcnt lgkmcnt(13)
	v_mfma_f32_16x16x32_bf16 v[10:13], v[74:77], v[148:151], v[10:13]
	s_waitcnt lgkmcnt(12)
	v_mfma_f32_16x16x32_bf16 v[14:17], v[78:81], v[148:151], v[14:17]
	s_waitcnt lgkmcnt(11)
	v_mfma_f32_16x16x32_bf16 v[18:21], v[82:85], v[148:151], v[18:21]
	s_waitcnt lgkmcnt(10)
	v_mfma_f32_16x16x32_bf16 v[22:25], v[86:89], v[148:151], v[22:25]
	s_waitcnt lgkmcnt(9)
	v_mfma_f32_16x16x32_bf16 v[26:29], v[90:93], v[148:151], v[26:29]
	s_waitcnt lgkmcnt(8)
	v_mfma_f32_16x16x32_bf16 v[30:33], v[94:97], v[148:151], v[30:33]
	ds_read_b128 v[66:69], v194 offset:192
	ds_read_b128 v[70:73], v194 offset:4544
	ds_read_b128 v[74:77], v194 offset:8896
	ds_read_b128 v[78:81], v194 offset:13248
	ds_read_b128 v[82:85], v194 offset:17600
	ds_read_b128 v[86:89], v194 offset:21952
	ds_read_b128 v[90:93], v194 offset:26304
	ds_read_b128 v[94:97], v194 offset:30656
	s_waitcnt lgkmcnt(15)
	v_mfma_f32_16x16x32_bf16 v[2:5], v[34:37], v[152:155], v[2:5]
	s_waitcnt lgkmcnt(14)
	v_mfma_f32_16x16x32_bf16 v[6:9], v[38:41], v[152:155], v[6:9]
	s_waitcnt lgkmcnt(13)
	v_mfma_f32_16x16x32_bf16 v[10:13], v[42:45], v[152:155], v[10:13]
	s_waitcnt lgkmcnt(12)
	v_mfma_f32_16x16x32_bf16 v[14:17], v[46:49], v[152:155], v[14:17]
	s_waitcnt lgkmcnt(11)
	v_mfma_f32_16x16x32_bf16 v[18:21], v[50:53], v[152:155], v[18:21]
	s_waitcnt lgkmcnt(10)
	v_mfma_f32_16x16x32_bf16 v[22:25], v[54:57], v[152:155], v[22:25]
	s_waitcnt lgkmcnt(9)
	v_mfma_f32_16x16x32_bf16 v[26:29], v[58:61], v[152:155], v[26:29]
	s_waitcnt lgkmcnt(8)
	v_mfma_f32_16x16x32_bf16 v[30:33], v[62:65], v[152:155], v[30:33]
	ds_read_b128 v[34:37], v194 offset:34816
	ds_read_b128 v[38:41], v194 offset:39168
	ds_read_b128 v[42:45], v194 offset:43520
	ds_read_b128 v[46:49], v194 offset:47872
	ds_read_b128 v[50:53], v194 offset:52224
	ds_read_b128 v[54:57], v194 offset:56576
	ds_read_b128 v[58:61], v194 offset:60928
	ds_read_b128 v[62:65], v194 offset:65280
	s_waitcnt lgkmcnt(15)
; __device__ __forceinline__ unsigned cvt_pk_bf16(float lo, float hi) { unsigned r; asm volatile("v_cvt_pk_bf16_f32 %0, %1, %2" : "=v"(r) : "v"(lo), "v"(hi)); return r; }
; #define LAS __attribute__((address_space(3)))
; #define MFMA16(a, b, c) __builtin_amdgcn_mfma_f32_16x16x32_bf16((a), (b), (c), 0, 0, 0)
; __device__ __forceinline__ void p2_block(LAS unsigned char* lds, const bf16_t* __restrict__ PROJ, bf16_t* __restrict__ ATT, bf16_t* __restrict__ SGU, const float* __restrict__ qn, const float* __restrict__ kn, ...
;     ...
;         for (int ks = 0; ks < 4; ++ks) if (ks < nks) {
;             const f32x4 wa = *(const f32x4*)(wrow + 32 * ks), wb = *(const f32x4*)(wrow + 32 * ks + 4);
;             const int j0 = 32 * ks + 8 * fq; float wv[8];
; #pragma unroll
;             for (int e = 0; e < 4; ++e) { wv[e] = (j0 + e <= irow) ? wa[e] : 0.f; wv[4 + e] = (j0 + 4 + e <= irow) ? wb[e] : 0.f; }
;             u32x4 ww; ww.x = cvt_pk_bf16(wv[0], wv[1]); ww.y = cvt_pk_bf16(wv[2], wv[3]); ww.z = cvt_pk_bf16(wv[4], wv[5]); ww.w = cvt_pk_bf16(wv[6], wv[7]);
;             const bf16x8 wf = __builtin_bit_cast(bf16x8, ww);
; #pragma unroll
;             for (int dt = 0; dt < 8; ++dt) { const bf16x8 af = *(const LAS bf16x8*)(VNT + (16 * dt + fr) * VN_STRIDE + (32 * ks + 8 * fq) * 2); acc[dt] = MFMA16(af, wf, acc[dt]); }
;         }
	v_mfma_f32_16x16x32_bf16 v[2:5], v[66:69], v[156:159], v[2:5]
	s_waitcnt lgkmcnt(14)
	v_mfma_f32_16x16x32_bf16 v[6:9], v[70:73], v[156:159], v[6:9]
	s_waitcnt lgkmcnt(13)
	v_mfma_f32_16x16x32_bf16 v[10:13], v[74:77], v[156:159], v[10:13]
	s_waitcnt lgkmcnt(12)
	v_mfma_f32_16x16x32_bf16 v[14:17], v[78:81], v[156:159], v[14:17]
	s_waitcnt lgkmcnt(11)
	v_mfma_f32_16x16x32_bf16 v[18:21], v[82:85], v[156:159], v[18:21]
	s_waitcnt lgkmcnt(10)
	v_mfma_f32_16x16x32_bf16 v[22:25], v[86:89], v[156:159], v[22:25]
	s_waitcnt lgkmcnt(9)
	v_mfma_f32_16x16x32_bf16 v[26:29], v[90:93], v[156:159], v[26:29]
	s_waitcnt lgkmcnt(8)
	v_mfma_f32_16x16x32_bf16 v[30:33], v[94:97], v[156:159], v[30:33]
	ds_read_b128 v[66:69], v194 offset:34880
	ds_read_b128 v[70:73], v194 offset:39232
	ds_read_b128 v[74:77], v194 offset:43584
	ds_read_b128 v[78:81], v194 offset:47936
	ds_read_b128 v[82:85], v194 offset:52288
	ds_read_b128 v[86:89], v194 offset:56640
	ds_read_b128 v[90:93], v194 offset:60992
	ds_read_b128 v[94:97], v194 offset:65344
	s_waitcnt lgkmcnt(15)
	v_mfma_f32_16x16x32_bf16 v[114:117], v[34:37], v[98:101], v[186:189]
	s_waitcnt lgkmcnt(14)
	v_mfma_f32_16x16x32_bf16 v[118:121], v[38:41], v[98:101], v[186:189]
	s_waitcnt lgkmcnt(13)
	v_mfma_f32_16x16x32_bf16 v[122:125], v[42:45], v[98:101], v[186:189]
	s_waitcnt lgkmcnt(12)
	v_mfma_f32_16x16x32_bf16 v[126:129], v[46:49], v[98:101], v[186:189]
	s_waitcnt lgkmcnt(11)
	v_mfma_f32_16x16x32_bf16 v[130:133], v[50:53], v[98:101], v[186:189]
	s_waitcnt lgkmcnt(10)
	v_mfma_f32_16x16x32_bf16 v[134:137], v[54:57], v[98:101], v[186:189]
	s_waitcnt lgkmcnt(9)
	v_mfma_f32_16x16x32_bf16 v[138:141], v[58:61], v[98:101], v[186:189]
	s_waitcnt lgkmcnt(8)
	v_mfma_f32_16x16x32_bf16 v[160:163], v[62:65], v[98:101], v[186:189]
	ds_read_b128 v[34:37], v194 offset:34944
	ds_read_b128 v[38:41], v194 offset:39296
	ds_read_b128 v[42:45], v194 offset:43648
	ds_read_b128 v[46:49], v194 offset:48000
	ds_read_b128 v[50:53], v194 offset:52352
	ds_read_b128 v[54:57], v194 offset:56704
	ds_read_b128 v[58:61], v194 offset:61056
	ds_read_b128 v[62:65], v194 offset:65408
	s_waitcnt lgkmcnt(15)
	v_mfma_f32_16x16x32_bf16 v[114:117], v[66:69], v[102:105], v[114:117]
	s_waitcnt lgkmcnt(14)
	v_mfma_f32_16x16x32_bf16 v[118:121], v[70:73], v[102:105], v[118:121]
	s_waitcnt lgkmcnt(13)
	v_mfma_f32_16x16x32_bf16 v[122:125], v[74:77], v[102:105], v[122:125]
	s_waitcnt lgkmcnt(12)
	v_mfma_f32_16x16x32_bf16 v[126:129], v[78:81], v[102:105], v[126:129]
	s_waitcnt lgkmcnt(11)
	v_mfma_f32_16x16x32_bf16 v[130:133], v[82:85], v[102:105], v[130:133]
	s_waitcnt lgkmcnt(10)
	v_mfma_f32_16x16x32_bf16 v[134:137], v[86:89], v[102:105], v[134:137]
	s_waitcnt lgkmcnt(9)
	v_mfma_f32_16x16x32_bf16 v[138:141], v[90:93], v[102:105], v[138:141]
	s_waitcnt lgkmcnt(8)
	v_mfma_f32_16x16x32_bf16 v[160:163], v[94:97], v[102:105], v[160:163]
	ds_read_b128 v[66:69], v194 offset:35008
	ds_read_b128 v[70:73], v194 offset:39360
	ds_read_b128 v[74:77], v194 offset:43712
	ds_read_b128 v[78:81], v194 offset:48064
	ds_read_b128 v[82:85], v194 offset:52416
	ds_read_b128 v[86:89], v194 offset:56768
	ds_read_b128 v[90:93], v194 offset:61120
	ds_read_b128 v[94:97], v194 offset:65472
	s_waitcnt lgkmcnt(15)
	v_mfma_f32_16x16x32_bf16 v[114:117], v[34:37], v[106:109], v[114:117]
	s_waitcnt lgkmcnt(14)
	v_mfma_f32_16x16x32_bf16 v[118:121], v[38:41], v[106:109], v[118:121]
	s_waitcnt lgkmcnt(13)
	v_mfma_f32_16x16x32_bf16 v[122:125], v[42:45], v[106:109], v[122:125]
	s_waitcnt lgkmcnt(12)
	v_mfma_f32_16x16x32_bf16 v[126:129], v[46:49], v[106:109], v[126:129]
	s_waitcnt lgkmcnt(11)
	v_mfma_f32_16x16x32_bf16 v[130:133], v[50:53], v[106:109], v[130:133]
	s_waitcnt lgkmcnt(10)
	v_mfma_f32_16x16x32_bf16 v[134:137], v[54:57], v[106:109], v[134:137]
	s_waitcnt lgkmcnt(9)
	v_mfma_f32_16x16x32_bf16 v[138:141], v[58:61], v[106:109], v[138:141]
	s_waitcnt lgkmcnt(8)
	v_mfma_f32_16x16x32_bf16 v[160:163], v[62:65], v[106:109], v[160:163]
	s_waitcnt lgkmcnt(7)
	v_mfma_f32_16x16x32_bf16 v[114:117], v[66:69], v[110:113], v[114:117]
	s_waitcnt lgkmcnt(6)
	v_mfma_f32_16x16x32_bf16 v[118:121], v[70:73], v[110:113], v[118:121]
	s_waitcnt lgkmcnt(5)
	v_mfma_f32_16x16x32_bf16 v[122:125], v[74:77], v[110:113], v[122:125]
	s_waitcnt lgkmcnt(4)
	v_mfma_f32_16x16x32_bf16 v[126:129], v[78:81], v[110:113], v[126:129]
	s_waitcnt lgkmcnt(3)
	v_mfma_f32_16x16x32_bf16 v[130:133], v[82:85], v[110:113], v[130:133]
	s_waitcnt lgkmcnt(2)
	v_mfma_f32_16x16x32_bf16 v[134:137], v[86:89], v[110:113], v[134:137]
	s_waitcnt lgkmcnt(1)
	v_mfma_f32_16x16x32_bf16 v[138:141], v[90:93], v[110:113], v[138:141]
	s_waitcnt lgkmcnt(0)
	v_mfma_f32_16x16x32_bf16 v[160:163], v[94:97], v[110:113], v[160:163]
	s_branch .Lsgu_epi

; __device__ __forceinline__ unsigned cvt_pk_bf16(float lo, float hi) { unsigned r; asm volatile("v_cvt_pk_bf16_f32 %0, %1, %2" : "=v"(r) : "v"(lo), "v"(hi)); return r; }
; __device__ __forceinline__ void tr_item(const float* __restrict__ W, int K, int N, bf16_t* WT, const float* __restrict__ kscale, int rowmode, int item, int lane) {
;     const int nblk = N >> 5, kb = item / nblk, nb = item - kb * nblk;
;     const int c = lane >> 3, q = lane & 7, k0 = kb * 64 + c * 8, n0 = nb * 32 + q * 4;
;     f32x4 v[8];
; #pragma unroll
;     for (int i = 0; i < 8; ++i) v[i] = __builtin_nontemporal_load((const f32x4*)(W + (size_t)(k0 + i) * N + n0));
;     if (kscale) { const f32x4 s0 = *(const f32x4*)(kscale + k0), s1 = *(const f32x4*)(kscale + k0 + 4);
; #pragma unroll
;         for (int i = 0; i < 4; ++i) { v[i] = v[i] * s0[i]; v[4 + i] = v[4 + i] * s1[i]; } }
;     int drow;
;     if (rowmode == 0) drow = n0;
;     else if (rowmode == 3) { const int g = n0 - pg8::C_GA; drow = g < 0 ? n0 : pg8::C_GA + (((g & 2047) >> 7) << 8) + ((g >> 11) << 7) + (g & 127); }
;     else drow = ((n0 >> 7) << 8) + (n0 & 127) + (rowmode == 2 ? 128 : 0);
; #pragma unroll
;     for (int e = 0; e < 4; ++e) { u32x4 o; o.x = cvt_pk_bf16(v[0][e], v[1][e]); o.y = cvt_pk_bf16(v[2][e], v[3][e]); o.z = cvt_pk_bf16(v[4][e], v[5][e]); o.w = cvt_pk_bf16(v[6][e], v[7][e]);
;         pg8::st16_wt(WT + (size_t)(drow + e) * K + k0, o); }
;     ...
;         else if (kind == 4) { W = a.in[14] + (size_t)l * 2048 * 5632; K = 2048; N = 5632; WT = (bf16_t*)(ws + WS_WGU + l * SZ_WGU); ks = a.in[13] + l * 2048; rm = 1; }
;         else if (kind == 5) { W = a.in[15] + (size_t)l * 2048 * 5632; K = 2048; N = 5632; WT = (bf16_t*)(ws + WS_WGU + l * SZ_WGU); ks = a.in[13] + l * 2048; rm = 2; }
;         else                { W = a.in[16] + (size_t)l * 5632 * 2048; K = 5632; N = 2048; WT = (bf16_t*)(ws + WS_WD + l * SZ_WD); }
;         const int nitems = (K >> 6) * (N >> 5);
;         int ilo = 0, ihi = nitems; if ((fmask >> mi) & 1u) { ilo = (nitems * flo) >> 4; ihi = (nitems * fhi) >> 4; }
;         const int cnt = ihi - ilo;
;         int first = (gw - base) % NGW; if (first < 0) first += NGW;
;         for (int it = first; it < cnt; it += NGW) tr_item(W, K, N, WT, ks, rm, ilo + it, lane);
.LBB0_400:
	s_or_b64 exec, exec, s[0:1]
	s_cmp_lg_u32 s64, 0
	s_cbranch_scc1 .Lcv_skip_2
	v_and_b32_e32 v106, 63, v204
	v_lshrrev_b32_e32 v107, 3, v106
	v_and_b32_e32 v108, 7, v106
	v_readfirstlane_b32 vcc_lo, v204
	s_nop 3
	s_lshr_b32 vcc_lo, vcc_lo, 6
	s_cmp_eq_u32 vcc_lo, 0
	s_cbranch_scc1 .Lcv_skip_2
	s_mul_i32 vcc_hi, s85, 7
	s_add_i32 vcc_lo, vcc_lo, vcc_hi
	s_add_i32 vcc_lo, vcc_lo, -1
	s_add_i32 vcc_lo, vcc_lo, 1792
	s_cmp_ge_u32 vcc_lo, 3520
	s_cbranch_scc1 .Lcv_2_0_n0
	s_sub_u32 vcc_lo, vcc_lo, 0
	v_mov_b32_e32 v113, vcc_lo
	v_mul_u32_u24_e32 v109, 0x5d18, v113
	v_lshrrev_b32_e32 v109, 22, v109
	v_mul_u32_u24_e32 v110, 0xb0, v109
	v_sub_u32_e32 v110, v113, v110
	v_lshlrev_b32_e32 v109, 6, v109
	v_lshl_add_u32 v109, v107, 3, v109
	v_lshlrev_b32_e32 v110, 5, v110
	v_lshl_add_u32 v110, v108, 2, v110
	v_mul_u32_u24_e32 v111, 0x5800, v109
	v_lshl_add_u32 v111, v110, 2, v111
	v_lshrrev_b32_e32 v112, 7, v110
	v_lshlrev_b32_e32 v112, 8, v112
	v_and_b32_e32 v113, 0x7f, v110
	v_add_u32_e32 v112, v112, v113
	v_lshlrev_b32_e32 v112, 12, v112
	v_lshl_add_u32 v112, v109, 1, v112
	v_lshlrev_b32_e32 v113, 2, v109
	v_readlane_b32 vcc_lo, v250, 28
	v_readlane_b32 vcc_hi, v250, 29
	s_nop 4
	global_load_dwordx4 v[98:101], v113, vcc
	global_load_dwordx4 v[102:105], v113, vcc offset:16
	v_readlane_b32 vcc_lo, v250, 30
	v_readlane_b32 vcc_hi, v250, 31
	s_nop 4
	global_load_dwordx4 v[66:69], v111, vcc nt
	v_add_u32_e32 v111, 0x5800, v111
	global_load_dwordx4 v[70:73], v111, vcc nt
	v_add_u32_e32 v111, 0x5800, v111
	global_load_dwordx4 v[74:77], v111, vcc nt
	v_add_u32_e32 v111, 0x5800, v111
	global_load_dwordx4 v[78:81], v111, vcc nt
	v_add_u32_e32 v111, 0x5800, v111
	global_load_dwordx4 v[82:85], v111, vcc nt
	v_add_u32_e32 v111, 0x5800, v111
	global_load_dwordx4 v[86:89], v111, vcc nt
	v_add_u32_e32 v111, 0x5800, v111
	global_load_dwordx4 v[90:93], v111, vcc nt
	v_add_u32_e32 v111, 0x5800, v111
	global_load_dwordx4 v[94:97], v111, vcc nt
	v_readlane_b32 vcc_lo, v250, 36
	v_readlane_b32 vcc_hi, v250, 37
	s_nop 3
	s_add_u32 vcc_lo, vcc_lo, 0x5dc0000
	s_addc_u32 vcc_hi, vcc_hi, 0
	s_waitcnt vmcnt(0)
	v_mul_f32_e32 v66, v66, v98
	v_mul_f32_e32 v67, v67, v98
	v_mul_f32_e32 v68, v68, v98
	v_mul_f32_e32 v69, v69, v98
	v_mul_f32_e32 v70, v70, v99
	v_mul_f32_e32 v71, v71, v99
	v_mul_f32_e32 v72, v72, v99
	v_mul_f32_e32 v73, v73, v99
	v_mul_f32_e32 v74, v74, v100
	v_mul_f32_e32 v75, v75, v100
	v_mul_f32_e32 v76, v76, v100
	v_mul_f32_e32 v77, v77, v100
	v_mul_f32_e32 v78, v78, v101
	v_mul_f32_e32 v79, v79, v101
	v_mul_f32_e32 v80, v80, v101
	v_mul_f32_e32 v81, v81, v101
	v_mul_f32_e32 v82, v82, v102
	v_mul_f32_e32 v83, v83, v102
	v_mul_f32_e32 v84, v84, v102
	v_mul_f32_e32 v85, v85, v102
	v_mul_f32_e32 v86, v86, v103
	v_mul_f32_e32 v87, v87, v103
	v_mul_f32_e32 v88, v88, v103
	v_mul_f32_e32 v89, v89, v103
	v_mul_f32_e32 v90, v90, v104
	v_mul_f32_e32 v91, v91, v104
	v_mul_f32_e32 v92, v92, v104
	v_mul_f32_e32 v93, v93, v104
	v_mul_f32_e32 v94, v94, v105
	v_mul_f32_e32 v95, v95, v105
	v_mul_f32_e32 v96, v96, v105
	v_mul_f32_e32 v97, v97, v105
	v_cvt_pk_bf16_f32 v114, v66, v70
	v_cvt_pk_bf16_f32 v115, v74, v78
	v_cvt_pk_bf16_f32 v116, v82, v86
	v_cvt_pk_bf16_f32 v117, v90, v94
	v_cvt_pk_bf16_f32 v118, v67, v71
	v_cvt_pk_bf16_f32 v119, v75, v79
	v_cvt_pk_bf16_f32 v120, v83, v87
	v_cvt_pk_bf16_f32 v121, v91, v95
	v_cvt_pk_bf16_f32 v122, v68, v72
	v_cvt_pk_bf16_f32 v123, v76, v80
	v_cvt_pk_bf16_f32 v124, v84, v88
	v_cvt_pk_bf16_f32 v125, v92, v96
	v_cvt_pk_bf16_f32 v126, v69, v73
	v_cvt_pk_bf16_f32 v127, v77, v81
	v_cvt_pk_bf16_f32 v128, v85, v89
	v_cvt_pk_bf16_f32 v129, v93, v97
	global_store_dwordx4 v112, v[114:117], vcc sc1
	v_add_u32_e32 v112, 0x1000, v112
	global_store_dwordx4 v112, v[118:121], vcc sc1
	v_add_u32_e32 v112, 0x1000, v112
	global_store_dwordx4 v112, v[122:125], vcc sc1
	v_add_u32_e32 v112, 0x1000, v112
	global_store_dwordx4 v112, v[126:129], vcc sc1
	s_branch .Lcv_done_2_0
; __device__ __forceinline__ unsigned cvt_pk_bf16(float lo, float hi) { unsigned r; asm volatile("v_cvt_pk_bf16_f32 %0, %1, %2" : "=v"(r) : "v"(lo), "v"(hi)); return r; }
; __device__ __forceinline__ void st16_wt(void* p, u32x4 v) { asm volatile("global_store_dwordx4 %0, %1, off sc1\n\ts_nop 1" :: "v"(p), "v"(v) : "memory"); }
; __device__ __forceinline__ void tr_item(const float* __restrict__ W, int K, int N, bf16_t* WT, const float* __restrict__ kscale, int rowmode, int item, int lane) {
;     const int nblk = N >> 5, kb = item / nblk, nb = item - kb * nblk;
;     const int c = lane >> 3, q = lane & 7, k0 = kb * 64 + c * 8, n0 = nb * 32 + q * 4;
;     f32x4 v[8];
; #pragma unroll
;     for (int i = 0; i < 8; ++i) v[i] = __builtin_nontemporal_load((const f32x4*)(W + (size_t)(k0 + i) * N + n0));
;     if (kscale) { const f32x4 s0 = *(const f32x4*)(kscale + k0), s1 = *(const f32x4*)(kscale + k0 + 4);
; #pragma unroll
;         for (int i = 0; i < 4; ++i) { v[i] = v[i] * s0[i]; v[4 + i] = v[4 + i] * s1[i]; } }
;     int drow;
;     if (rowmode == 0) drow = n0;
;     else if (rowmode == 3) { const int g = n0 - pg8::C_GA; drow = g < 0 ? n0 : pg8::C_GA + (((g & 2047) >> 7) << 8) + ((g >> 11) << 7) + (g & 127); }
;     else drow = ((n0 >> 7) << 8) + (n0 & 127) + (rowmode == 2 ? 128 : 0);
; #pragma unroll
;     for (int e = 0; e < 4; ++e) { u32x4 o; o.x = cvt_pk_bf16(v[0][e], v[1][e]); o.y = cvt_pk_bf16(v[2][e], v[3][e]); o.z = cvt_pk_bf16(v[4][e], v[5][e]); o.w = cvt_pk_bf16(v[6][e], v[7][e]);
;         pg8::st16_wt(WT + (size_t)(drow + e) * K + k0, o); }
;     ...
;         else if (kind == 4) { W = a.in[14] + (size_t)l * 2048 * 5632; K = 2048; N = 5632; WT = (bf16_t*)(ws + WS_WGU + l * SZ_WGU); ks = a.in[13] + l * 2048; rm = 1; }
;         else if (kind == 5) { W = a.in[15] + (size_t)l * 2048 * 5632; K = 2048; N = 5632; WT = (bf16_t*)(ws + WS_WGU + l * SZ_WGU); ks = a.in[13] + l * 2048; rm = 2; }
.Lcv_2_0_n0:
	s_sub_u32 vcc_lo, vcc_lo, 3520
	v_mov_b32_e32 v113, vcc_lo
	v_mul_u32_u24_e32 v109, 0x5d18, v113
	v_lshrrev_b32_e32 v109, 22, v109
	v_mul_u32_u24_e32 v110, 0xb0, v109
	v_sub_u32_e32 v110, v113, v110
	v_lshlrev_b32_e32 v109, 6, v109
	v_lshl_add_u32 v109, v107, 3, v109
	v_lshlrev_b32_e32 v110, 5, v110
	v_lshl_add_u32 v110, v108, 2, v110
	v_mul_u32_u24_e32 v111, 0x5800, v109
	v_lshl_add_u32 v111, v110, 2, v111
	v_add_u32_e32 v111, 0x2c00000, v111
	v_lshrrev_b32_e32 v112, 7, v110
	v_lshlrev_b32_e32 v112, 8, v112
	v_and_b32_e32 v113, 0x7f, v110
	v_add_u32_e32 v112, v112, v113
	v_lshlrev_b32_e32 v112, 12, v112
	v_lshl_add_u32 v112, v109, 1, v112
	v_lshlrev_b32_e32 v113, 2, v109
	v_add_u32_e32 v113, 0x2000, v113
	v_readlane_b32 vcc_lo, v250, 28
	v_readlane_b32 vcc_hi, v250, 29
	s_nop 4
	global_load_dwordx4 v[98:101], v113, vcc
	global_load_dwordx4 v[102:105], v113, vcc offset:16
	v_readlane_b32 vcc_lo, v250, 30
	v_readlane_b32 vcc_hi, v250, 31
	s_nop 4
	global_load_dwordx4 v[66:69], v111, vcc nt
	v_add_u32_e32 v111, 0x5800, v111
	global_load_dwordx4 v[70:73], v111, vcc nt
	v_add_u32_e32 v111, 0x5800, v111
	global_load_dwordx4 v[74:77], v111, vcc nt
	v_add_u32_e32 v111, 0x5800, v111
	global_load_dwordx4 v[78:81], v111, vcc nt
	v_add_u32_e32 v111, 0x5800, v111
	global_load_dwordx4 v[82:85], v111, vcc nt
	v_add_u32_e32 v111, 0x5800, v111
	global_load_dwordx4 v[86:89], v111, vcc nt
	v_add_u32_e32 v111, 0x5800, v111
	global_load_dwordx4 v[90:93], v111, vcc nt
	v_add_u32_e32 v111, 0x5800, v111
	global_load_dwordx4 v[94:97], v111, vcc nt
	v_readlane_b32 vcc_lo, v250, 36
	v_readlane_b32 vcc_hi, v250, 37
	s_nop 3
	s_add_u32 vcc_lo, vcc_lo, 0x89c0000
	s_addc_u32 vcc_hi, vcc_hi, 0
	s_waitcnt vmcnt(0)
	v_mul_f32_e32 v66, v66, v98
	v_mul_f32_e32 v67, v67, v98
	v_mul_f32_e32 v68, v68, v98
	v_mul_f32_e32 v69, v69, v98
	v_mul_f32_e32 v70, v70, v99
	v_mul_f32_e32 v71, v71, v99
	v_mul_f32_e32 v72, v72, v99
	v_mul_f32_e32 v73, v73, v99
	v_mul_f32_e32 v74, v74, v100
	v_mul_f32_e32 v75, v75, v100
	v_mul_f32_e32 v76, v76, v100
	v_mul_f32_e32 v77, v77, v100
	v_mul_f32_e32 v78, v78, v101
	v_mul_f32_e32 v79, v79, v101
	v_mul_f32_e32 v80, v80, v101
	v_mul_f32_e32 v81, v81, v101
	v_mul_f32_e32 v82, v82, v102
	v_mul_f32_e32 v83, v83, v102
	v_mul_f32_e32 v84, v84, v102
	v_mul_f32_e32 v85, v85, v102
	v_mul_f32_e32 v86, v86, v103
	v_mul_f32_e32 v87, v87, v103
	v_mul_f32_e32 v88, v88, v103
	v_mul_f32_e32 v89, v89, v103
	v_mul_f32_e32 v90, v90, v104
	v_mul_f32_e32 v91, v91, v104
	v_mul_f32_e32 v92, v92, v104
	v_mul_f32_e32 v93, v93, v104
	v_mul_f32_e32 v94, v94, v105
	v_mul_f32_e32 v95, v95, v105
	v_mul_f32_e32 v96, v96, v105
	v_mul_f32_e32 v97, v97, v105
	v_cvt_pk_bf16_f32 v114, v66, v70
	v_cvt_pk_bf16_f32 v115, v74, v78
	v_cvt_pk_bf16_f32 v116, v82, v86
	v_cvt_pk_bf16_f32 v117, v90, v94
	v_cvt_pk_bf16_f32 v118, v67, v71
	v_cvt_pk_bf16_f32 v119, v75, v79
	v_cvt_pk_bf16_f32 v120, v83, v87
	v_cvt_pk_bf16_f32 v121, v91, v95
	v_cvt_pk_bf16_f32 v122, v68, v72
	v_cvt_pk_bf16_f32 v123, v76, v80
	v_cvt_pk_bf16_f32 v124, v84, v88
	v_cvt_pk_bf16_f32 v125, v92, v96
	v_cvt_pk_bf16_f32 v126, v69, v73
	v_cvt_pk_bf16_f32 v127, v77, v81
	v_cvt_pk_bf16_f32 v128, v85, v89
	v_cvt_pk_bf16_f32 v129, v93, v97
	global_store_dwordx4 v112, v[114:117], vcc sc1
	v_add_u32_e32 v112, 0x1000, v112
	global_store_dwordx4 v112, v[118:121], vcc sc1
	v_add_u32_e32 v112, 0x1000, v112
	global_store_dwordx4 v112, v[122:125], vcc sc1
	v_add_u32_e32 v112, 0x1000, v112
	global_store_dwordx4 v112, v[126:129], vcc sc1
.Lcv_done_2_0:
.Lcv_skip_2:
	s_mov_b64 s[0:1], 0
	s_waitcnt lgkmcnt(0)
	s_barrier

; __device__ __forceinline__ unsigned cvt_pk_bf16(float lo, float hi) { unsigned r; asm volatile("v_cvt_pk_bf16_f32 %0, %1, %2" : "=v"(r) : "v"(lo), "v"(hi)); return r; }
; __device__ __forceinline__ void st16_wt(void* p, u32x4 v) { asm volatile("global_store_dwordx4 %0, %1, off sc1\n\ts_nop 1" :: "v"(p), "v"(v) : "memory"); }
; __device__ __forceinline__ void tr_item(const float* __restrict__ W, int K, int N, bf16_t* WT, const float* __restrict__ kscale, int rowmode, int item, int lane) {
;     const int nblk = N >> 5, kb = item / nblk, nb = item - kb * nblk;
;     const int c = lane >> 3, q = lane & 7, k0 = kb * 64 + c * 8, n0 = nb * 32 + q * 4;
;     f32x4 v[8];
; #pragma unroll
;     for (int i = 0; i < 8; ++i) v[i] = __builtin_nontemporal_load((const f32x4*)(W + (size_t)(k0 + i) * N + n0));
;     if (kscale) { const f32x4 s0 = *(const f32x4*)(kscale + k0), s1 = *(const f32x4*)(kscale + k0 + 4);
; #pragma unroll
;         for (int i = 0; i < 4; ++i) { v[i] = v[i] * s0[i]; v[4 + i] = v[4 + i] * s1[i]; } }
;     int drow;
;     if (rowmode == 0) drow = n0;
;     else if (rowmode == 3) { const int g = n0 - pg8::C_GA; drow = g < 0 ? n0 : pg8::C_GA + (((g & 2047) >> 7) << 8) + ((g >> 11) << 7) + (g & 127); }
;     else drow = ((n0 >> 7) << 8) + (n0 & 127) + (rowmode == 2 ? 128 : 0);
; #pragma unroll
;     for (int e = 0; e < 4; ++e) { u32x4 o; o.x = cvt_pk_bf16(v[0][e], v[1][e]); o.y = cvt_pk_bf16(v[2][e], v[3][e]); o.z = cvt_pk_bf16(v[4][e], v[5][e]); o.w = cvt_pk_bf16(v[6][e], v[7][e]);
;         pg8::st16_wt(WT + (size_t)(drow + e) * K + k0, o); }
;     ...
;         else if (kind == 4) { W = a.in[14] + (size_t)l * 2048 * 5632; K = 2048; N = 5632; WT = (bf16_t*)(ws + WS_WGU + l * SZ_WGU); ks = a.in[13] + l * 2048; rm = 1; }
;         else if (kind == 5) { W = a.in[15] + (size_t)l * 2048 * 5632; K = 2048; N = 5632; WT = (bf16_t*)(ws + WS_WGU + l * SZ_WGU); ks = a.in[13] + l * 2048; rm = 2; }
.LBB0_524:
	s_or_b64 exec, exec, s[0:1]
	s_cmp_lg_u32 s64, 0
	s_cbranch_scc1 .Lcv_skip_3
	v_and_b32_e32 v106, 63, v204
	v_lshrrev_b32_e32 v107, 3, v106
	v_and_b32_e32 v108, 7, v106
	v_readfirstlane_b32 vcc_lo, v204
	s_nop 3
	s_lshr_b32 vcc_lo, vcc_lo, 6
	s_cmp_eq_u32 vcc_lo, 0
	s_cbranch_scc1 .Lcv_skip_3
	s_mul_i32 vcc_hi, s85, 7
	s_add_i32 vcc_lo, vcc_lo, vcc_hi
	s_add_i32 vcc_lo, vcc_lo, -1
	s_add_i32 vcc_lo, vcc_lo, 3584
	s_sub_u32 vcc_lo, vcc_lo, 3520
	v_mov_b32_e32 v113, vcc_lo
	v_mul_u32_u24_e32 v109, 0x5d18, v113
	v_lshrrev_b32_e32 v109, 22, v109
	v_mul_u32_u24_e32 v110, 0xb0, v109
	v_sub_u32_e32 v110, v113, v110
	v_lshlrev_b32_e32 v109, 6, v109
	v_lshl_add_u32 v109, v107, 3, v109
	v_lshlrev_b32_e32 v110, 5, v110
	v_lshl_add_u32 v110, v108, 2, v110
	v_mul_u32_u24_e32 v111, 0x5800, v109
	v_lshl_add_u32 v111, v110, 2, v111
	v_add_u32_e32 v111, 0x2c00000, v111
	v_lshrrev_b32_e32 v112, 7, v110
	v_lshlrev_b32_e32 v112, 8, v112
	v_and_b32_e32 v113, 0x7f, v110
	v_add_u32_e32 v112, v112, v113
	v_lshlrev_b32_e32 v112, 12, v112
	v_lshl_add_u32 v112, v109, 1, v112
	v_lshlrev_b32_e32 v113, 2, v109
	v_add_u32_e32 v113, 0x2000, v113
	v_readlane_b32 vcc_lo, v250, 28
	v_readlane_b32 vcc_hi, v250, 29
	s_nop 4
	global_load_dwordx4 v[98:101], v113, vcc
	global_load_dwordx4 v[102:105], v113, vcc offset:16
	v_readlane_b32 vcc_lo, v250, 30
	v_readlane_b32 vcc_hi, v250, 31
	s_nop 4
	global_load_dwordx4 v[66:69], v111, vcc nt
	v_add_u32_e32 v111, 0x5800, v111
	global_load_dwordx4 v[70:73], v111, vcc nt
	v_add_u32_e32 v111, 0x5800, v111
	global_load_dwordx4 v[74:77], v111, vcc nt
	v_add_u32_e32 v111, 0x5800, v111
	global_load_dwordx4 v[78:81], v111, vcc nt
	v_add_u32_e32 v111, 0x5800, v111
	global_load_dwordx4 v[82:85], v111, vcc nt
	v_add_u32_e32 v111, 0x5800, v111
	global_load_dwordx4 v[86:89], v111, vcc nt
	v_add_u32_e32 v111, 0x5800, v111
	global_load_dwordx4 v[90:93], v111, vcc nt
	v_add_u32_e32 v111, 0x5800, v111
	global_load_dwordx4 v[94:97], v111, vcc nt
	v_readlane_b32 vcc_lo, v250, 36
	v_readlane_b32 vcc_hi, v250, 37
	s_nop 3
	s_add_u32 vcc_lo, vcc_lo, 0x89c0000
	s_addc_u32 vcc_hi, vcc_hi, 0
	s_waitcnt vmcnt(0)
	v_mul_f32_e32 v66, v66, v98
	v_mul_f32_e32 v67, v67, v98
	v_mul_f32_e32 v68, v68, v98
	v_mul_f32_e32 v69, v69, v98
	v_mul_f32_e32 v70, v70, v99
	v_mul_f32_e32 v71, v71, v99
	v_mul_f32_e32 v72, v72, v99
	v_mul_f32_e32 v73, v73, v99
	v_mul_f32_e32 v74, v74, v100
	v_mul_f32_e32 v75, v75, v100
	v_mul_f32_e32 v76, v76, v100
	v_mul_f32_e32 v77, v77, v100
	v_mul_f32_e32 v78, v78, v101
	v_mul_f32_e32 v79, v79, v101
	v_mul_f32_e32 v80, v80, v101
	v_mul_f32_e32 v81, v81, v101
	v_mul_f32_e32 v82, v82, v102
	v_mul_f32_e32 v83, v83, v102
	v_mul_f32_e32 v84, v84, v102
	v_mul_f32_e32 v85, v85, v102
	v_mul_f32_e32 v86, v86, v103
	v_mul_f32_e32 v87, v87, v103
	v_mul_f32_e32 v88, v88, v103
	v_mul_f32_e32 v89, v89, v103
	v_mul_f32_e32 v90, v90, v104
	v_mul_f32_e32 v91, v91, v104
	v_mul_f32_e32 v92, v92, v104
	v_mul_f32_e32 v93, v93, v104
	v_mul_f32_e32 v94, v94, v105
	v_mul_f32_e32 v95, v95, v105
	v_mul_f32_e32 v96, v96, v105
	v_mul_f32_e32 v97, v97, v105
	v_cvt_pk_bf16_f32 v114, v66, v70
	v_cvt_pk_bf16_f32 v115, v74, v78
	v_cvt_pk_bf16_f32 v116, v82, v86
	v_cvt_pk_bf16_f32 v117, v90, v94
	v_cvt_pk_bf16_f32 v118, v67, v71
	v_cvt_pk_bf16_f32 v119, v75, v79
	v_cvt_pk_bf16_f32 v120, v83, v87
	v_cvt_pk_bf16_f32 v121, v91, v95
	v_cvt_pk_bf16_f32 v122, v68, v72
	v_cvt_pk_bf16_f32 v123, v76, v80
	v_cvt_pk_bf16_f32 v124, v84, v88
	v_cvt_pk_bf16_f32 v125, v92, v96
	v_cvt_pk_bf16_f32 v126, v69, v73
	v_cvt_pk_bf16_f32 v127, v77, v81
	v_cvt_pk_bf16_f32 v128, v85, v89
	v_cvt_pk_bf16_f32 v129, v93, v97
	global_store_dwordx4 v112, v[114:117], vcc sc1
	v_add_u32_e32 v112, 0x1000, v112
	global_store_dwordx4 v112, v[118:121], vcc sc1
	v_add_u32_e32 v112, 0x1000, v112
	global_store_dwordx4 v112, v[122:125], vcc sc1
	v_add_u32_e32 v112, 0x1000, v112
	global_store_dwordx4 v112, v[126:129], vcc sc1

; __device__ __forceinline__ unsigned cvt_pk_bf16(float lo, float hi) { unsigned r; asm volatile("v_cvt_pk_bf16_f32 %0, %1, %2" : "=v"(r) : "v"(lo), "v"(hi)); return r; }
; __device__ __forceinline__ void st16_wt(void* p, u32x4 v) { asm volatile("global_store_dwordx4 %0, %1, off sc1\n\ts_nop 1" :: "v"(p), "v"(v) : "memory"); }
; __device__ __forceinline__ void tr_item(const float* __restrict__ W, int K, int N, bf16_t* WT, const float* __restrict__ kscale, int rowmode, int item, int lane) {
;     const int nblk = N >> 5, kb = item / nblk, nb = item - kb * nblk;
;     const int c = lane >> 3, q = lane & 7, k0 = kb * 64 + c * 8, n0 = nb * 32 + q * 4;
;     f32x4 v[8];
; #pragma unroll
;     for (int i = 0; i < 8; ++i) v[i] = __builtin_nontemporal_load((const f32x4*)(W + (size_t)(k0 + i) * N + n0));
;     if (kscale) { const f32x4 s0 = *(const f32x4*)(kscale + k0), s1 = *(const f32x4*)(kscale + k0 + 4);
; #pragma unroll
;         for (int i = 0; i < 4; ++i) { v[i] = v[i] * s0[i]; v[4 + i] = v[4 + i] * s1[i]; } }
;     int drow;
;     if (rowmode == 0) drow = n0;
;     else if (rowmode == 3) { const int g = n0 - pg8::C_GA; drow = g < 0 ? n0 : pg8::C_GA + (((g & 2047) >> 7) << 8) + ((g >> 11) << 7) + (g & 127); }
;     else drow = ((n0 >> 7) << 8) + (n0 & 127) + (rowmode == 2 ? 128 : 0);
; #pragma unroll
;     for (int e = 0; e < 4; ++e) { u32x4 o; o.x = cvt_pk_bf16(v[0][e], v[1][e]); o.y = cvt_pk_bf16(v[2][e], v[3][e]); o.z = cvt_pk_bf16(v[4][e], v[5][e]); o.w = cvt_pk_bf16(v[6][e], v[7][e]);
;         pg8::st16_wt(WT + (size_t)(drow + e) * K + k0, o); }
;     ...
;         else if (kind == 4) { W = a.in[14] + (size_t)l * 2048 * 5632; K = 2048; N = 5632; WT = (bf16_t*)(ws + WS_WGU + l * SZ_WGU); ks = a.in[13] + l * 2048; rm = 1; }
;         else if (kind == 5) { W = a.in[15] + (size_t)l * 2048 * 5632; K = 2048; N = 5632; WT = (bf16_t*)(ws + WS_WGU + l * SZ_WGU); ks = a.in[13] + l * 2048; rm = 2; }
.LBB0_632:
	s_or_b64 exec, exec, s[0:1]
	s_cmp_lg_u32 s64, 0
	s_cbranch_scc1 .Lcv_skip_4
	v_and_b32_e32 v106, 63, v204
	v_lshrrev_b32_e32 v107, 3, v106
	v_and_b32_e32 v108, 7, v106
	v_readfirstlane_b32 vcc_lo, v204
	s_nop 3
	s_lshr_b32 vcc_lo, vcc_lo, 6
	s_cmp_eq_u32 vcc_lo, 0
	s_cbranch_scc1 .Lcv_skip_4
	s_mul_i32 vcc_hi, s85, 7
	s_add_i32 vcc_lo, vcc_lo, vcc_hi
	s_add_i32 vcc_lo, vcc_lo, -1
	s_cmp_ge_u32 vcc_lo, 1664
	s_cbranch_scc1 .Lcv_skip_4
	s_add_i32 vcc_lo, vcc_lo, 5376
	s_sub_u32 vcc_lo, vcc_lo, 3520
	v_mov_b32_e32 v113, vcc_lo
	v_mul_u32_u24_e32 v109, 0x5d18, v113
	v_lshrrev_b32_e32 v109, 22, v109
	v_mul_u32_u24_e32 v110, 0xb0, v109
	v_sub_u32_e32 v110, v113, v110
	v_lshlrev_b32_e32 v109, 6, v109
	v_lshl_add_u32 v109, v107, 3, v109
	v_lshlrev_b32_e32 v110, 5, v110
	v_lshl_add_u32 v110, v108, 2, v110
	v_mul_u32_u24_e32 v111, 0x5800, v109
	v_lshl_add_u32 v111, v110, 2, v111
	v_add_u32_e32 v111, 0x2c00000, v111
	v_lshrrev_b32_e32 v112, 7, v110
	v_lshlrev_b32_e32 v112, 8, v112
	v_and_b32_e32 v113, 0x7f, v110
	v_add_u32_e32 v112, v112, v113
	v_lshlrev_b32_e32 v112, 12, v112
	v_lshl_add_u32 v112, v109, 1, v112
	v_lshlrev_b32_e32 v113, 2, v109
	v_add_u32_e32 v113, 0x2000, v113
	v_readlane_b32 vcc_lo, v250, 28
	v_readlane_b32 vcc_hi, v250, 29
	s_nop 4
	global_load_dwordx4 v[98:101], v113, vcc
	global_load_dwordx4 v[102:105], v113, vcc offset:16
	v_readlane_b32 vcc_lo, v250, 30
	v_readlane_b32 vcc_hi, v250, 31
	s_nop 4
	global_load_dwordx4 v[66:69], v111, vcc nt
	v_add_u32_e32 v111, 0x5800, v111
	global_load_dwordx4 v[70:73], v111, vcc nt
	v_add_u32_e32 v111, 0x5800, v111
	global_load_dwordx4 v[74:77], v111, vcc nt
	v_add_u32_e32 v111, 0x5800, v111
	global_load_dwordx4 v[78:81], v111, vcc nt
	v_add_u32_e32 v111, 0x5800, v111
	global_load_dwordx4 v[82:85], v111, vcc nt
	v_add_u32_e32 v111, 0x5800, v111
	global_load_dwordx4 v[86:89], v111, vcc nt
	v_add_u32_e32 v111, 0x5800, v111
	global_load_dwordx4 v[90:93], v111, vcc nt
	v_add_u32_e32 v111, 0x5800, v111
	global_load_dwordx4 v[94:97], v111, vcc nt
	v_readlane_b32 vcc_lo, v250, 36
	v_readlane_b32 vcc_hi, v250, 37
	s_nop 3
	s_add_u32 vcc_lo, vcc_lo, 0x89c0000
	s_addc_u32 vcc_hi, vcc_hi, 0
	s_waitcnt vmcnt(0)
	v_mul_f32_e32 v66, v66, v98
	v_mul_f32_e32 v67, v67, v98
	v_mul_f32_e32 v68, v68, v98
	v_mul_f32_e32 v69, v69, v98
	v_mul_f32_e32 v70, v70, v99
	v_mul_f32_e32 v71, v71, v99
	v_mul_f32_e32 v72, v72, v99
	v_mul_f32_e32 v73, v73, v99
	v_mul_f32_e32 v74, v74, v100
	v_mul_f32_e32 v75, v75, v100
	v_mul_f32_e32 v76, v76, v100
	v_mul_f32_e32 v77, v77, v100
	v_mul_f32_e32 v78, v78, v101
	v_mul_f32_e32 v79, v79, v101
	v_mul_f32_e32 v80, v80, v101
	v_mul_f32_e32 v81, v81, v101
	v_mul_f32_e32 v82, v82, v102
	v_mul_f32_e32 v83, v83, v102
	v_mul_f32_e32 v84, v84, v102
	v_mul_f32_e32 v85, v85, v102
	v_mul_f32_e32 v86, v86, v103
	v_mul_f32_e32 v87, v87, v103
	v_mul_f32_e32 v88, v88, v103
	v_mul_f32_e32 v89, v89, v103
	v_mul_f32_e32 v90, v90, v104
	v_mul_f32_e32 v91, v91, v104
	v_mul_f32_e32 v92, v92, v104
	v_mul_f32_e32 v93, v93, v104
	v_mul_f32_e32 v94, v94, v105
	v_mul_f32_e32 v95, v95, v105
	v_mul_f32_e32 v96, v96, v105
	v_mul_f32_e32 v97, v97, v105
	v_cvt_pk_bf16_f32 v114, v66, v70
	v_cvt_pk_bf16_f32 v115, v74, v78
	v_cvt_pk_bf16_f32 v116, v82, v86
	v_cvt_pk_bf16_f32 v117, v90, v94
	v_cvt_pk_bf16_f32 v118, v67, v71
	v_cvt_pk_bf16_f32 v119, v75, v79
	v_cvt_pk_bf16_f32 v120, v83, v87
	v_cvt_pk_bf16_f32 v121, v91, v95
	v_cvt_pk_bf16_f32 v122, v68, v72
	v_cvt_pk_bf16_f32 v123, v76, v80
	v_cvt_pk_bf16_f32 v124, v84, v88
	v_cvt_pk_bf16_f32 v125, v92, v96
	v_cvt_pk_bf16_f32 v126, v69, v73
	v_cvt_pk_bf16_f32 v127, v77, v81
	v_cvt_pk_bf16_f32 v128, v85, v89
	v_cvt_pk_bf16_f32 v129, v93, v97
	global_store_dwordx4 v112, v[114:117], vcc sc1
	v_add_u32_e32 v112, 0x1000, v112
	global_store_dwordx4 v112, v[118:121], vcc sc1
	v_add_u32_e32 v112, 0x1000, v112
	global_store_dwordx4 v112, v[122:125], vcc sc1
	v_add_u32_e32 v112, 0x1000, v112
	global_store_dwordx4 v112, v[126:129], vcc sc1
